# P1 epilogue: nt only on f32 cache outputs, gates and Qb; Qa/Qm/Qi/K/V bf16 keep default caching (read at P2 item starts)
# speedup vs baseline: 1.1900x; 1.0018x over previous
.LBB0_242:
	s_or_saveexec_b64 s[8:9], s[8:9]
	s_mov_b64 s[68:69], 0
	s_xor_b64 exec, exec, s[8:9]
	s_cbranch_execz .LBB0_250
	v_cmp_lt_i32_e32 vcc, 1, v177
	s_mov_b64 s[72:73], 0
	s_mov_b64 s[68:69], -1
	s_mov_b64 s[74:75], s[66:67]
	s_and_saveexec_b64 s[0:1], vcc
	s_cbranch_execz .LBB0_249
	v_cmp_lt_i32_e32 vcc, 2, v177
	s_mov_b64 s[72:73], -1
	s_mov_b64 s[74:75], s[66:67]
	s_and_saveexec_b64 s[68:69], vcc
	s_cbranch_execz .LBB0_248
	v_cmp_lt_i32_e32 vcc, 3, v177
	s_mov_b64 s[74:75], -1
	s_and_saveexec_b64 s[72:73], vcc
	s_cbranch_execz .LBB0_247
	v_mbcnt_hi_u32_b32 v128, -1, v204
	v_and_b32_e32 v130, 64, v128
	v_xor_b32_e32 v129, 8, v128
	v_add_u32_e32 v130, 64, v130
	v_cmp_lt_i32_e32 vcc, v129, v130
	v_readlane_b32 s36, v253, 26
	v_ashrrev_i32_e32 v137, 31, v136
	v_cndmask_b32_e32 v128, v128, v129, vcc
	v_cmp_gt_u32_e32 vcc, 8, v176
	v_readlane_b32 s37, v253, 27
	v_lshl_add_u32 v149, v178, 2, v211
	v_lshlrev_b32_e32 v150, 2, v128
	v_cndmask_b32_e64 v148, 1.0, -1.0, vcc
	v_readlane_b32 s38, v253, 28
	v_readlane_b32 s39, v253, 29
	v_readlane_b32 s40, v253, 30
	v_readlane_b32 s41, v253, 31
	v_readlane_b32 s42, v253, 32
	v_readlane_b32 s43, v253, 33
	v_readlane_b32 s44, v253, 34
	v_readlane_b32 s45, v253, 35
	v_readlane_b32 s46, v253, 36
	v_readlane_b32 s47, v253, 37
	v_readlane_b32 s48, v253, 38
	v_readlane_b32 s49, v253, 39
	v_readlane_b32 s50, v253, 40
	v_readlane_b32 s51, v253, 41
	v_lshl_add_u64 v[128:129], v[136:137], 1, s[36:37]
	v_lshlrev_b32_e32 v130, 5, v174
	v_and_b32_e32 v134, 0xe0, v130
	v_lshl_add_u64 v[130:131], s[58:59], 0, v[134:135]
	v_lshlrev_b32_e32 v134, 10, v178
	v_and_b32_e32 v134, 0x1c00, v134
	v_lshl_add_u64 v[140:141], v[130:131], 0, v[134:135]
	s_mov_b64 s[26:27], 0x80100
	v_lshl_add_u64 v[138:139], v[140:141], 0, s[26:27]
	v_lshl_add_u64 v[142:143], v[140:141], 0, s[84:85]
	v_add_co_u32_e32 v140, vcc, s33, v140
	ds_bpermute_b32 v134, v150, v124
	s_nop 0
	v_addc_co_u32_e32 v141, vcc, 0, v141, vcc
	global_load_dwordx4 v[144:147], v[140:141], off
	global_load_dwordx4 v[152:155], v[142:143], off offset:16
	ds_bpermute_b32 v137, v150, v120
	ds_bpermute_b32 v151, v150, v116
	s_waitcnt lgkmcnt(2)
	v_mul_f32_e32 v157, v148, v134
	v_mov_b32_e32 v156, v124
	ds_bpermute_b32 v158, v150, v112
	ds_bpermute_b32 v162, v150, v117
	v_mov_b32_e32 v160, v125
	ds_bpermute_b32 v163, v150, v113
	s_waitcnt vmcnt(1)
	v_pk_mul_f32 v[144:145], v[156:157], v[144:145]
	s_nop 0
	v_add_f32_e32 v134, v144, v145
	s_waitcnt lgkmcnt(4)
	v_mul_f32_e32 v145, v148, v137
	v_mov_b32_e32 v144, v120
	v_pk_mul_f32 v[144:145], v[144:145], v[146:147]
	v_mul_f32_e32 v134, 0x3e38aa3b, v134
	v_add_f32_e32 v137, v144, v145
	s_waitcnt lgkmcnt(3)
	v_mul_f32_e32 v145, v148, v151
	v_mov_b32_e32 v144, v116
	s_waitcnt vmcnt(0)
	v_pk_mul_f32 v[144:145], v[144:145], v[152:153]
	v_mul_f32_e32 v137, 0x3e38aa3b, v137
	v_add_f32_e32 v146, v144, v145
	s_waitcnt lgkmcnt(2)
	v_mul_f32_e32 v145, v148, v158
	v_mov_b32_e32 v144, v112
	v_pk_mul_f32 v[144:145], v[144:145], v[154:155]
	global_load_dwordx4 v[152:155], v[140:141], off offset:256
	global_load_dwordx4 v[156:159], v[138:139], off offset:16
	v_add_f32_e32 v147, v144, v145
	v_mul_f32_e32 v151, 0x3e38aa3b, v146
	v_cvt_pk_bf16_f32 v146, v134, v137
	ds_bpermute_b32 v137, v150, v125
	v_mul_f32_e32 v147, 0x3e38aa3b, v147
	v_cvt_pk_bf16_f32 v147, v151, v147
	ds_bpermute_b32 v151, v150, v121
	v_mad_i64_i32 v[144:145], s[24:25], v149, s13, v[128:129]
	s_waitcnt lgkmcnt(1)
	v_mul_f32_e32 v161, v148, v137
	v_or_b32_e32 v134, 1, v149
	global_store_dwordx2 v[144:145], v[146:147], off nt
	s_waitcnt vmcnt(2)
	v_pk_mul_f32 v[152:153], v[160:161], v[152:153]
	s_nop 0
	v_add_f32_e32 v137, v152, v153
	s_waitcnt lgkmcnt(0)
	v_mul_f32_e32 v153, v148, v151
	v_mov_b32_e32 v152, v121
	v_pk_mul_f32 v[152:153], v[152:153], v[154:155]
	s_nop 0
	v_add_f32_e32 v151, v152, v153
	v_mul_f32_e32 v153, v148, v162
	v_mov_b32_e32 v152, v117
	s_waitcnt vmcnt(1)
	v_pk_mul_f32 v[152:153], v[152:153], v[156:157]
	s_nop 0
	v_add_f32_e32 v154, v152, v153
	v_mul_f32_e32 v153, v148, v163
	v_mov_b32_e32 v152, v113
	v_pk_mul_f32 v[144:145], v[152:153], v[158:159]
	v_mul_f32_e32 v147, 0x3e38aa3b, v154
	v_add_f32_e32 v146, v144, v145
	v_mad_i64_i32 v[144:145], s[24:25], v134, s13, v[128:129]
	v_mul_f32_e32 v134, 0x3e38aa3b, v137
	v_mul_f32_e32 v137, 0x3e38aa3b, v151
	v_mul_f32_e32 v151, 0x3e38aa3b, v146
	v_cvt_pk_bf16_f32 v146, v134, v137
	v_cvt_pk_bf16_f32 v147, v147, v151
	global_store_dwordx2 v[144:145], v[146:147], off nt
	v_or_b32_e32 v137, 2, v149
	v_lshlrev_b32_e32 v134, 8, v137
	v_and_b32_e32 v134, 0x1e00, v134
	v_lshl_add_u64 v[144:145], v[130:131], 0, v[134:135]
	v_add_co_u32_e32 v160, vcc, s33, v144
	v_lshl_add_u64 v[152:153], v[144:145], 0, s[84:85]
	s_nop 0
	v_addc_co_u32_e32 v161, vcc, 0, v145, vcc
	v_lshl_add_u64 v[156:157], v[144:145], 0, s[26:27]
	global_load_dwordx4 v[144:147], v[160:161], off
	s_nop 0
	global_load_dwordx4 v[152:155], v[152:153], off offset:16
	ds_bpermute_b32 v134, v150, v126
	ds_bpermute_b32 v151, v150, v122
	ds_bpermute_b32 v162, v150, v118
	v_mov_b32_e32 v158, v126
	ds_bpermute_b32 v163, v150, v114
	s_waitcnt lgkmcnt(3)
	v_mul_f32_e32 v159, v148, v134
	ds_bpermute_b32 v164, v150, v119
	ds_bpermute_b32 v165, v150, v115
	s_waitcnt vmcnt(1)
	v_pk_mul_f32 v[144:145], v[158:159], v[144:145]
	s_nop 0
	v_add_f32_e32 v134, v144, v145
	s_waitcnt lgkmcnt(4)
	v_mul_f32_e32 v145, v148, v151
	v_mov_b32_e32 v144, v122
	v_pk_mul_f32 v[144:145], v[144:145], v[146:147]
	v_mul_f32_e32 v134, 0x3e38aa3b, v134
	v_add_f32_e32 v146, v144, v145
	s_waitcnt lgkmcnt(3)
	v_mul_f32_e32 v145, v148, v162
	v_mov_b32_e32 v144, v118
	s_waitcnt vmcnt(0)
	v_pk_mul_f32 v[144:145], v[144:145], v[152:153]
	v_mov_b32_e32 v162, v127
	v_add_f32_e32 v147, v144, v145
	s_waitcnt lgkmcnt(2)
	v_mul_f32_e32 v145, v148, v163
	v_mov_b32_e32 v144, v114
	v_pk_mul_f32 v[144:145], v[144:145], v[154:155]
	global_load_dwordx4 v[152:155], v[160:161], off offset:256
	s_nop 0
	global_load_dwordx4 v[156:159], v[156:157], off offset:16
	v_add_f32_e32 v151, v144, v145
	v_mad_i64_i32 v[144:145], s[24:25], v137, s13, v[128:129]
	v_mul_f32_e32 v137, 0x3e38aa3b, v146
	v_cvt_pk_bf16_f32 v146, v134, v137
	ds_bpermute_b32 v137, v150, v127
	v_mul_f32_e32 v147, 0x3e38aa3b, v147
	v_mul_f32_e32 v151, 0x3e38aa3b, v151
	v_cvt_pk_bf16_f32 v147, v147, v151
	ds_bpermute_b32 v151, v150, v123
	s_waitcnt lgkmcnt(1)
	v_mul_f32_e32 v163, v148, v137
	v_or_b32_e32 v134, 3, v149
	global_store_dwordx2 v[144:145], v[146:147], off nt
	s_waitcnt vmcnt(2)
	v_pk_mul_f32 v[152:153], v[162:163], v[152:153]
	s_nop 0
	v_add_f32_e32 v137, v152, v153
	s_waitcnt lgkmcnt(0)
	v_mul_f32_e32 v153, v148, v151
	v_mov_b32_e32 v152, v123
	v_pk_mul_f32 v[152:153], v[152:153], v[154:155]
	s_nop 0
	v_add_f32_e32 v151, v152, v153
	v_mul_f32_e32 v153, v148, v164
	v_mov_b32_e32 v152, v119
	s_waitcnt vmcnt(1)
	v_pk_mul_f32 v[152:153], v[152:153], v[156:157]
	s_nop 0
	v_add_f32_e32 v154, v152, v153
	v_mul_f32_e32 v153, v148, v165
	v_mov_b32_e32 v152, v115
	v_pk_mul_f32 v[144:145], v[152:153], v[158:159]
	v_mul_f32_e32 v147, 0x3e38aa3b, v154
	v_add_f32_e32 v146, v144, v145
	v_mad_i64_i32 v[144:145], s[24:25], v134, s13, v[128:129]
	v_mul_f32_e32 v134, 0x3e38aa3b, v137
	v_mul_f32_e32 v137, 0x3e38aa3b, v151
	v_mul_f32_e32 v151, 0x3e38aa3b, v146
	v_cvt_pk_bf16_f32 v146, v134, v137
	v_cvt_pk_bf16_f32 v147, v147, v151
	global_store_dwordx2 v[144:145], v[146:147], off nt
	v_add_u32_e32 v137, 16, v149
	v_lshlrev_b32_e32 v134, 8, v137
	v_and_b32_e32 v134, 0x1c00, v134
	v_lshl_add_u64 v[144:145], v[130:131], 0, v[134:135]
	v_add_co_u32_e32 v160, vcc, s33, v144
	v_lshl_add_u64 v[152:153], v[144:145], 0, s[84:85]
	s_nop 0
	v_addc_co_u32_e32 v161, vcc, 0, v145, vcc
	v_lshl_add_u64 v[156:157], v[144:145], 0, s[26:27]
	global_load_dwordx4 v[144:147], v[160:161], off
	s_nop 0
	global_load_dwordx4 v[152:155], v[152:153], off offset:16
	ds_bpermute_b32 v134, v150, v108
	ds_bpermute_b32 v151, v150, v104
	ds_bpermute_b32 v162, v150, v100
	v_mov_b32_e32 v158, v108
	ds_bpermute_b32 v163, v150, v96
	s_waitcnt lgkmcnt(3)
	v_mul_f32_e32 v159, v148, v134
	ds_bpermute_b32 v164, v150, v101
	ds_bpermute_b32 v165, v150, v97
	s_waitcnt vmcnt(1)
	v_pk_mul_f32 v[144:145], v[158:159], v[144:145]
	s_nop 0
	v_add_f32_e32 v134, v144, v145
	s_waitcnt lgkmcnt(4)
	v_mul_f32_e32 v145, v148, v151
	v_mov_b32_e32 v144, v104
	v_pk_mul_f32 v[144:145], v[144:145], v[146:147]
	v_mul_f32_e32 v134, 0x3e38aa3b, v134
	v_add_f32_e32 v146, v144, v145
	s_waitcnt lgkmcnt(3)
	v_mul_f32_e32 v145, v148, v162
	v_mov_b32_e32 v144, v100
	s_waitcnt vmcnt(0)
	v_pk_mul_f32 v[144:145], v[144:145], v[152:153]
	v_mov_b32_e32 v162, v109
	v_add_f32_e32 v147, v144, v145
	s_waitcnt lgkmcnt(2)
	v_mul_f32_e32 v145, v148, v163
	v_mov_b32_e32 v144, v96
	v_pk_mul_f32 v[144:145], v[144:145], v[154:155]
	global_load_dwordx4 v[152:155], v[160:161], off offset:256
	s_nop 0
	global_load_dwordx4 v[156:159], v[156:157], off offset:16
	v_add_f32_e32 v151, v144, v145
	v_mad_i64_i32 v[144:145], s[24:25], v137, s13, v[128:129]
	v_mul_f32_e32 v137, 0x3e38aa3b, v146
	v_cvt_pk_bf16_f32 v146, v134, v137
	ds_bpermute_b32 v137, v150, v109
	v_mul_f32_e32 v147, 0x3e38aa3b, v147
	v_mul_f32_e32 v151, 0x3e38aa3b, v151
	v_cvt_pk_bf16_f32 v147, v147, v151
	ds_bpermute_b32 v151, v150, v105
	s_waitcnt lgkmcnt(1)
	v_mul_f32_e32 v163, v148, v137
	v_add_u32_e32 v134, 17, v149
	global_store_dwordx2 v[144:145], v[146:147], off nt
	s_waitcnt vmcnt(2)
	v_pk_mul_f32 v[152:153], v[162:163], v[152:153]
	s_nop 0
	v_add_f32_e32 v137, v152, v153
	s_waitcnt lgkmcnt(0)
	v_mul_f32_e32 v153, v148, v151
	v_mov_b32_e32 v152, v105
	v_pk_mul_f32 v[152:153], v[152:153], v[154:155]
	s_nop 0
	v_add_f32_e32 v151, v152, v153
	v_mul_f32_e32 v153, v148, v164
	v_mov_b32_e32 v152, v101
	s_waitcnt vmcnt(1)
	v_pk_mul_f32 v[152:153], v[152:153], v[156:157]
	s_nop 0
	v_add_f32_e32 v154, v152, v153
	v_mul_f32_e32 v153, v148, v165
	v_mov_b32_e32 v152, v97
	v_pk_mul_f32 v[144:145], v[152:153], v[158:159]
	v_mul_f32_e32 v147, 0x3e38aa3b, v154
	v_add_f32_e32 v146, v144, v145
	v_mad_i64_i32 v[144:145], s[24:25], v134, s13, v[128:129]
	v_mul_f32_e32 v134, 0x3e38aa3b, v137
	v_mul_f32_e32 v137, 0x3e38aa3b, v151
	v_mul_f32_e32 v151, 0x3e38aa3b, v146
	v_cvt_pk_bf16_f32 v146, v134, v137
	v_cvt_pk_bf16_f32 v147, v147, v151
	global_store_dwordx2 v[144:145], v[146:147], off nt
	v_add_u32_e32 v137, 18, v149
	v_lshlrev_b32_e32 v134, 8, v137
	v_and_b32_e32 v134, 0x1e00, v134
	v_lshl_add_u64 v[144:145], v[130:131], 0, v[134:135]
	v_add_co_u32_e32 v160, vcc, s33, v144
	v_lshl_add_u64 v[152:153], v[144:145], 0, s[84:85]
	s_nop 0
	v_addc_co_u32_e32 v161, vcc, 0, v145, vcc
	v_lshl_add_u64 v[156:157], v[144:145], 0, s[26:27]
	global_load_dwordx4 v[144:147], v[160:161], off
	s_nop 0
	global_load_dwordx4 v[152:155], v[152:153], off offset:16
	ds_bpermute_b32 v134, v150, v110
	ds_bpermute_b32 v151, v150, v106
	ds_bpermute_b32 v162, v150, v102
	v_mov_b32_e32 v158, v110
	ds_bpermute_b32 v163, v150, v98
	s_waitcnt lgkmcnt(3)
	v_mul_f32_e32 v159, v148, v134
	ds_bpermute_b32 v164, v150, v103
	ds_bpermute_b32 v165, v150, v99
	s_waitcnt vmcnt(1)
	v_pk_mul_f32 v[144:145], v[158:159], v[144:145]
	s_nop 0
	v_add_f32_e32 v134, v144, v145
	s_waitcnt lgkmcnt(4)
	v_mul_f32_e32 v145, v148, v151
	v_mov_b32_e32 v144, v106
	v_pk_mul_f32 v[144:145], v[144:145], v[146:147]
	v_mul_f32_e32 v134, 0x3e38aa3b, v134
	v_add_f32_e32 v146, v144, v145
	s_waitcnt lgkmcnt(3)
	v_mul_f32_e32 v145, v148, v162
	v_mov_b32_e32 v144, v102
	s_waitcnt vmcnt(0)
	v_pk_mul_f32 v[144:145], v[144:145], v[152:153]
	v_mov_b32_e32 v162, v111
	v_add_f32_e32 v147, v144, v145
	s_waitcnt lgkmcnt(2)
	v_mul_f32_e32 v145, v148, v163
	v_mov_b32_e32 v144, v98
	v_pk_mul_f32 v[144:145], v[144:145], v[154:155]
	global_load_dwordx4 v[152:155], v[160:161], off offset:256
	s_nop 0
	global_load_dwordx4 v[156:159], v[156:157], off offset:16
	v_add_f32_e32 v151, v144, v145
	v_mad_i64_i32 v[144:145], s[24:25], v137, s13, v[128:129]
	v_mul_f32_e32 v137, 0x3e38aa3b, v146
	v_cvt_pk_bf16_f32 v146, v134, v137
	ds_bpermute_b32 v137, v150, v111
	v_mul_f32_e32 v147, 0x3e38aa3b, v147
	v_mul_f32_e32 v151, 0x3e38aa3b, v151
	v_cvt_pk_bf16_f32 v147, v147, v151
	ds_bpermute_b32 v151, v150, v107
	s_waitcnt lgkmcnt(1)
	v_mul_f32_e32 v163, v148, v137
	v_add_u32_e32 v134, 19, v149
	global_store_dwordx2 v[144:145], v[146:147], off nt
	s_waitcnt vmcnt(2)
	v_pk_mul_f32 v[152:153], v[162:163], v[152:153]
	s_nop 0
	v_add_f32_e32 v137, v152, v153
	s_waitcnt lgkmcnt(0)
	v_mul_f32_e32 v153, v148, v151
	v_mov_b32_e32 v152, v107
	v_pk_mul_f32 v[152:153], v[152:153], v[154:155]
	s_nop 0
	v_add_f32_e32 v151, v152, v153
	v_mul_f32_e32 v153, v148, v164
	v_mov_b32_e32 v152, v103
	s_waitcnt vmcnt(1)
	v_pk_mul_f32 v[152:153], v[152:153], v[156:157]
	s_nop 0
	v_add_f32_e32 v154, v152, v153
	v_mul_f32_e32 v153, v148, v165
	v_mov_b32_e32 v152, v99
	v_pk_mul_f32 v[144:145], v[152:153], v[158:159]
	v_mul_f32_e32 v147, 0x3e38aa3b, v154
	v_add_f32_e32 v146, v144, v145
	v_mad_i64_i32 v[144:145], s[24:25], v134, s13, v[128:129]
	v_mul_f32_e32 v134, 0x3e38aa3b, v137
	v_mul_f32_e32 v137, 0x3e38aa3b, v151
	v_mul_f32_e32 v151, 0x3e38aa3b, v146
	v_cvt_pk_bf16_f32 v146, v134, v137
	v_cvt_pk_bf16_f32 v147, v147, v151
	global_store_dwordx2 v[144:145], v[146:147], off nt
	v_add_u32_e32 v134, 32, v149
	global_load_dwordx4 v[144:147], v[140:141], off
	global_load_dwordx4 v[152:155], v[142:143], off offset:16
	ds_bpermute_b32 v137, v150, v92
	ds_bpermute_b32 v151, v150, v88
	ds_bpermute_b32 v158, v150, v84
	v_mov_b32_e32 v156, v92
	ds_bpermute_b32 v159, v150, v80
	s_waitcnt lgkmcnt(3)
	v_mul_f32_e32 v157, v148, v137
	ds_bpermute_b32 v162, v150, v85
	v_mov_b32_e32 v160, v93
	ds_bpermute_b32 v163, v150, v81
	s_waitcnt vmcnt(1)
	v_pk_mul_f32 v[144:145], v[156:157], v[144:145]
	s_nop 0
	v_add_f32_e32 v137, v144, v145
	s_waitcnt lgkmcnt(4)
	v_mul_f32_e32 v145, v148, v151
	v_mov_b32_e32 v144, v88
	v_pk_mul_f32 v[144:145], v[144:145], v[146:147]
	s_nop 0
	v_add_f32_e32 v146, v144, v145
	s_waitcnt lgkmcnt(3)
	v_mul_f32_e32 v145, v148, v158
	v_mov_b32_e32 v144, v84
	s_waitcnt vmcnt(0)
	v_pk_mul_f32 v[144:145], v[144:145], v[152:153]
	s_nop 0
	v_add_f32_e32 v147, v144, v145
	s_waitcnt lgkmcnt(2)
	v_mul_f32_e32 v145, v148, v159
	v_mov_b32_e32 v144, v80
	v_pk_mul_f32 v[144:145], v[144:145], v[154:155]
	global_load_dwordx4 v[152:155], v[140:141], off offset:256
	global_load_dwordx4 v[156:159], v[138:139], off offset:16
	v_add_f32_e32 v151, v144, v145
	v_mad_i64_i32 v[144:145], s[24:25], v134, s13, v[128:129]
	v_mul_f32_e32 v134, 0x3e38aa3b, v137
	v_mul_f32_e32 v137, 0x3e38aa3b, v146
	v_cvt_pk_bf16_f32 v146, v134, v137
	ds_bpermute_b32 v137, v150, v93
	v_mul_f32_e32 v147, 0x3e38aa3b, v147
	v_mul_f32_e32 v151, 0x3e38aa3b, v151
	v_cvt_pk_bf16_f32 v147, v147, v151
	ds_bpermute_b32 v151, v150, v89
	s_waitcnt lgkmcnt(1)
	v_mul_f32_e32 v161, v148, v137
	v_add_u32_e32 v134, 33, v149
	global_store_dwordx2 v[144:145], v[146:147], off nt
	s_waitcnt vmcnt(2)
	v_pk_mul_f32 v[152:153], v[160:161], v[152:153]
	s_nop 0
	v_add_f32_e32 v137, v152, v153
	s_waitcnt lgkmcnt(0)
	v_mul_f32_e32 v153, v148, v151
	v_mov_b32_e32 v152, v89
	v_pk_mul_f32 v[152:153], v[152:153], v[154:155]
	s_nop 0
	v_add_f32_e32 v151, v152, v153
	v_mul_f32_e32 v153, v148, v162
	v_mov_b32_e32 v152, v85
	s_waitcnt vmcnt(1)
	v_pk_mul_f32 v[152:153], v[152:153], v[156:157]
	s_nop 0
	v_add_f32_e32 v154, v152, v153
	v_mul_f32_e32 v153, v148, v163
	v_mov_b32_e32 v152, v81
	v_pk_mul_f32 v[144:145], v[152:153], v[158:159]
	v_mul_f32_e32 v147, 0x3e38aa3b, v154
	v_add_f32_e32 v146, v144, v145
	v_mad_i64_i32 v[144:145], s[24:25], v134, s13, v[128:129]
	v_mul_f32_e32 v134, 0x3e38aa3b, v137
	v_mul_f32_e32 v137, 0x3e38aa3b, v151
	v_mul_f32_e32 v151, 0x3e38aa3b, v146
	v_cvt_pk_bf16_f32 v146, v134, v137
	v_cvt_pk_bf16_f32 v147, v147, v151
	global_store_dwordx2 v[144:145], v[146:147], off nt
	v_add_u32_e32 v137, 34, v149
	v_lshlrev_b32_e32 v134, 8, v137
	v_and_b32_e32 v134, 0x1e00, v134
	v_lshl_add_u64 v[144:145], v[130:131], 0, v[134:135]
	v_add_co_u32_e32 v160, vcc, s33, v144
	v_lshl_add_u64 v[152:153], v[144:145], 0, s[84:85]
	s_nop 0
	v_addc_co_u32_e32 v161, vcc, 0, v145, vcc
	v_lshl_add_u64 v[156:157], v[144:145], 0, s[26:27]
	global_load_dwordx4 v[144:147], v[160:161], off
	s_nop 0
	global_load_dwordx4 v[152:155], v[152:153], off offset:16
	ds_bpermute_b32 v134, v150, v94
	ds_bpermute_b32 v151, v150, v90
	ds_bpermute_b32 v162, v150, v86
	v_mov_b32_e32 v158, v94
	ds_bpermute_b32 v163, v150, v82
	s_waitcnt lgkmcnt(3)
	v_mul_f32_e32 v159, v148, v134
	ds_bpermute_b32 v164, v150, v87
	ds_bpermute_b32 v165, v150, v83
	s_waitcnt vmcnt(1)
	v_pk_mul_f32 v[144:145], v[158:159], v[144:145]
	s_nop 0
	v_add_f32_e32 v134, v144, v145
	s_waitcnt lgkmcnt(4)
	v_mul_f32_e32 v145, v148, v151
	v_mov_b32_e32 v144, v90
	v_pk_mul_f32 v[144:145], v[144:145], v[146:147]
	v_mul_f32_e32 v134, 0x3e38aa3b, v134
	v_add_f32_e32 v146, v144, v145
	s_waitcnt lgkmcnt(3)
	v_mul_f32_e32 v145, v148, v162
	v_mov_b32_e32 v144, v86
	s_waitcnt vmcnt(0)
	v_pk_mul_f32 v[144:145], v[144:145], v[152:153]
	v_mov_b32_e32 v162, v95
	v_add_f32_e32 v147, v144, v145
	s_waitcnt lgkmcnt(2)
	v_mul_f32_e32 v145, v148, v163
	v_mov_b32_e32 v144, v82
	v_pk_mul_f32 v[144:145], v[144:145], v[154:155]
	global_load_dwordx4 v[152:155], v[160:161], off offset:256
	s_nop 0
	global_load_dwordx4 v[156:159], v[156:157], off offset:16
	v_add_f32_e32 v151, v144, v145
	v_mad_i64_i32 v[144:145], s[24:25], v137, s13, v[128:129]
	v_mul_f32_e32 v137, 0x3e38aa3b, v146
	v_cvt_pk_bf16_f32 v146, v134, v137
	ds_bpermute_b32 v137, v150, v95
	v_mul_f32_e32 v147, 0x3e38aa3b, v147
	v_mul_f32_e32 v151, 0x3e38aa3b, v151
	v_cvt_pk_bf16_f32 v147, v147, v151
	ds_bpermute_b32 v151, v150, v91
	s_waitcnt lgkmcnt(1)
	v_mul_f32_e32 v163, v148, v137
	v_add_u32_e32 v134, 35, v149
	global_store_dwordx2 v[144:145], v[146:147], off nt
	s_waitcnt vmcnt(2)
	v_pk_mul_f32 v[152:153], v[162:163], v[152:153]
	s_nop 0
	v_add_f32_e32 v137, v152, v153
	s_waitcnt lgkmcnt(0)
	v_mul_f32_e32 v153, v148, v151
	v_mov_b32_e32 v152, v91
	v_pk_mul_f32 v[152:153], v[152:153], v[154:155]
	s_nop 0
	v_add_f32_e32 v151, v152, v153
	v_mul_f32_e32 v153, v148, v164
	v_mov_b32_e32 v152, v87
	s_waitcnt vmcnt(1)
	v_pk_mul_f32 v[152:153], v[152:153], v[156:157]
	s_nop 0
	v_add_f32_e32 v154, v152, v153
	v_mul_f32_e32 v153, v148, v165
	v_mov_b32_e32 v152, v83
	v_pk_mul_f32 v[144:145], v[152:153], v[158:159]
	v_mul_f32_e32 v147, 0x3e38aa3b, v154
	v_add_f32_e32 v146, v144, v145
	v_mad_i64_i32 v[144:145], s[24:25], v134, s13, v[128:129]
	v_mul_f32_e32 v134, 0x3e38aa3b, v137
	v_mul_f32_e32 v137, 0x3e38aa3b, v151
	v_mul_f32_e32 v151, 0x3e38aa3b, v146
	v_cvt_pk_bf16_f32 v146, v134, v137
	v_cvt_pk_bf16_f32 v147, v147, v151
	global_store_dwordx2 v[144:145], v[146:147], off nt
	v_add_u32_e32 v137, 48, v149
	v_lshlrev_b32_e32 v134, 8, v137
	v_and_b32_e32 v134, 0x1c00, v134
	v_lshl_add_u64 v[144:145], v[130:131], 0, v[134:135]
	v_add_co_u32_e32 v160, vcc, s33, v144
	v_lshl_add_u64 v[152:153], v[144:145], 0, s[84:85]
	s_nop 0
	v_addc_co_u32_e32 v161, vcc, 0, v145, vcc
	v_lshl_add_u64 v[156:157], v[144:145], 0, s[26:27]
	global_load_dwordx4 v[144:147], v[160:161], off
	s_nop 0
	global_load_dwordx4 v[152:155], v[152:153], off offset:16
	ds_bpermute_b32 v134, v150, v76
	ds_bpermute_b32 v151, v150, v72
	ds_bpermute_b32 v162, v150, v68
	v_mov_b32_e32 v158, v76
	ds_bpermute_b32 v163, v150, v64
	s_waitcnt lgkmcnt(3)
	v_mul_f32_e32 v159, v148, v134
	ds_bpermute_b32 v164, v150, v69
	ds_bpermute_b32 v165, v150, v65
	s_waitcnt vmcnt(1)
	v_pk_mul_f32 v[144:145], v[158:159], v[144:145]
	s_nop 0
	v_add_f32_e32 v134, v144, v145
	s_waitcnt lgkmcnt(4)
	v_mul_f32_e32 v145, v148, v151
	v_mov_b32_e32 v144, v72
	v_pk_mul_f32 v[144:145], v[144:145], v[146:147]
	v_mul_f32_e32 v134, 0x3e38aa3b, v134
	v_add_f32_e32 v146, v144, v145
	s_waitcnt lgkmcnt(3)
	v_mul_f32_e32 v145, v148, v162
	v_mov_b32_e32 v144, v68
	s_waitcnt vmcnt(0)
	v_pk_mul_f32 v[144:145], v[144:145], v[152:153]
	v_mov_b32_e32 v162, v77
	v_add_f32_e32 v147, v144, v145
	s_waitcnt lgkmcnt(2)
	v_mul_f32_e32 v145, v148, v163
	v_mov_b32_e32 v144, v64
	v_pk_mul_f32 v[144:145], v[144:145], v[154:155]
	global_load_dwordx4 v[152:155], v[160:161], off offset:256
	s_nop 0
	global_load_dwordx4 v[156:159], v[156:157], off offset:16
	v_add_f32_e32 v151, v144, v145
	v_mad_i64_i32 v[144:145], s[24:25], v137, s13, v[128:129]
	v_mul_f32_e32 v137, 0x3e38aa3b, v146
	v_cvt_pk_bf16_f32 v146, v134, v137
	ds_bpermute_b32 v137, v150, v77
	v_mul_f32_e32 v147, 0x3e38aa3b, v147
	v_mul_f32_e32 v151, 0x3e38aa3b, v151
	v_cvt_pk_bf16_f32 v147, v147, v151
	ds_bpermute_b32 v151, v150, v73
	s_waitcnt lgkmcnt(1)
	v_mul_f32_e32 v163, v148, v137
	v_add_u32_e32 v134, 49, v149
	global_store_dwordx2 v[144:145], v[146:147], off nt
	s_waitcnt vmcnt(2)
	v_pk_mul_f32 v[152:153], v[162:163], v[152:153]
	s_nop 0
	v_add_f32_e32 v137, v152, v153
	s_waitcnt lgkmcnt(0)
	v_mul_f32_e32 v153, v148, v151
	v_mov_b32_e32 v152, v73
	v_pk_mul_f32 v[152:153], v[152:153], v[154:155]
	s_nop 0
	v_add_f32_e32 v151, v152, v153
	v_mul_f32_e32 v153, v148, v164
	v_mov_b32_e32 v152, v69
	s_waitcnt vmcnt(1)
	v_pk_mul_f32 v[152:153], v[152:153], v[156:157]
	s_nop 0
	v_add_f32_e32 v154, v152, v153
	v_mul_f32_e32 v153, v148, v165
	v_mov_b32_e32 v152, v65
	v_pk_mul_f32 v[144:145], v[152:153], v[158:159]
	v_mul_f32_e32 v147, 0x3e38aa3b, v154
	v_add_f32_e32 v146, v144, v145
	v_mad_i64_i32 v[144:145], s[24:25], v134, s13, v[128:129]
	v_mul_f32_e32 v134, 0x3e38aa3b, v137
	v_mul_f32_e32 v137, 0x3e38aa3b, v151
	v_mul_f32_e32 v151, 0x3e38aa3b, v146
	v_cvt_pk_bf16_f32 v146, v134, v137
	v_cvt_pk_bf16_f32 v147, v147, v151
	global_store_dwordx2 v[144:145], v[146:147], off nt
	v_add_u32_e32 v137, 50, v149
	v_lshlrev_b32_e32 v134, 8, v137
	v_and_b32_e32 v134, 0x1e00, v134
	v_lshl_add_u64 v[144:145], v[130:131], 0, v[134:135]
	v_add_co_u32_e32 v160, vcc, s33, v144
	v_lshl_add_u64 v[152:153], v[144:145], 0, s[84:85]
	s_nop 0
	v_addc_co_u32_e32 v161, vcc, 0, v145, vcc
	v_lshl_add_u64 v[156:157], v[144:145], 0, s[26:27]
	global_load_dwordx4 v[144:147], v[160:161], off
	s_nop 0
	global_load_dwordx4 v[152:155], v[152:153], off offset:16
	ds_bpermute_b32 v134, v150, v78
	ds_bpermute_b32 v151, v150, v74
	ds_bpermute_b32 v162, v150, v70
	v_mov_b32_e32 v158, v78
	ds_bpermute_b32 v163, v150, v66
	s_waitcnt lgkmcnt(3)
	v_mul_f32_e32 v159, v148, v134
	ds_bpermute_b32 v164, v150, v71
	ds_bpermute_b32 v165, v150, v67
	s_waitcnt vmcnt(1)
	v_pk_mul_f32 v[144:145], v[158:159], v[144:145]
	s_nop 0
	v_add_f32_e32 v134, v144, v145
	s_waitcnt lgkmcnt(4)
	v_mul_f32_e32 v145, v148, v151
	v_mov_b32_e32 v144, v74
	v_pk_mul_f32 v[144:145], v[144:145], v[146:147]
	v_mul_f32_e32 v134, 0x3e38aa3b, v134
	v_add_f32_e32 v146, v144, v145
	s_waitcnt lgkmcnt(3)
	v_mul_f32_e32 v145, v148, v162
	v_mov_b32_e32 v144, v70
	s_waitcnt vmcnt(0)
	v_pk_mul_f32 v[144:145], v[144:145], v[152:153]
	v_mov_b32_e32 v162, v79
	v_add_f32_e32 v147, v144, v145
	s_waitcnt lgkmcnt(2)
	v_mul_f32_e32 v145, v148, v163
	v_mov_b32_e32 v144, v66
	v_pk_mul_f32 v[144:145], v[144:145], v[154:155]
	global_load_dwordx4 v[152:155], v[160:161], off offset:256
	s_nop 0
	global_load_dwordx4 v[156:159], v[156:157], off offset:16
	v_add_f32_e32 v151, v144, v145
	v_mad_i64_i32 v[144:145], s[24:25], v137, s13, v[128:129]
	v_mul_f32_e32 v137, 0x3e38aa3b, v146
	v_cvt_pk_bf16_f32 v146, v134, v137
	ds_bpermute_b32 v137, v150, v79
	v_mul_f32_e32 v147, 0x3e38aa3b, v147
	v_mul_f32_e32 v151, 0x3e38aa3b, v151
	v_cvt_pk_bf16_f32 v147, v147, v151
	ds_bpermute_b32 v151, v150, v75
	s_waitcnt lgkmcnt(1)
	v_mul_f32_e32 v163, v148, v137
	v_add_u32_e32 v134, 51, v149
	global_store_dwordx2 v[144:145], v[146:147], off nt
	s_waitcnt vmcnt(2)
	v_pk_mul_f32 v[152:153], v[162:163], v[152:153]
	s_nop 0
	v_add_f32_e32 v137, v152, v153
	s_waitcnt lgkmcnt(0)
	v_mul_f32_e32 v153, v148, v151
	v_mov_b32_e32 v152, v75
	v_pk_mul_f32 v[152:153], v[152:153], v[154:155]
	s_nop 0
	v_add_f32_e32 v151, v152, v153
	v_mul_f32_e32 v153, v148, v164
	v_mov_b32_e32 v152, v71
	s_waitcnt vmcnt(1)
	v_pk_mul_f32 v[152:153], v[152:153], v[156:157]
	s_nop 0
	v_add_f32_e32 v154, v152, v153
	v_mul_f32_e32 v153, v148, v165
	v_mov_b32_e32 v152, v67
	v_pk_mul_f32 v[144:145], v[152:153], v[158:159]
	v_mul_f32_e32 v147, 0x3e38aa3b, v154
	v_add_f32_e32 v146, v144, v145
	v_mad_i64_i32 v[144:145], s[24:25], v134, s13, v[128:129]
	v_mul_f32_e32 v134, 0x3e38aa3b, v137
	v_mul_f32_e32 v137, 0x3e38aa3b, v151
	v_mul_f32_e32 v151, 0x3e38aa3b, v146
	v_cvt_pk_bf16_f32 v146, v134, v137
	v_cvt_pk_bf16_f32 v147, v147, v151
	global_store_dwordx2 v[144:145], v[146:147], off nt
	v_add_u32_e32 v134, 64, v149
	global_load_dwordx4 v[144:147], v[140:141], off
	global_load_dwordx4 v[152:155], v[142:143], off offset:16
	ds_bpermute_b32 v137, v150, v60
	ds_bpermute_b32 v151, v150, v56
	ds_bpermute_b32 v158, v150, v52
	v_mov_b32_e32 v156, v60
	ds_bpermute_b32 v159, v150, v48
	s_waitcnt lgkmcnt(3)
	v_mul_f32_e32 v157, v148, v137
	ds_bpermute_b32 v162, v150, v53
	v_mov_b32_e32 v160, v61
	ds_bpermute_b32 v163, v150, v49
	s_waitcnt vmcnt(1)
	v_pk_mul_f32 v[144:145], v[156:157], v[144:145]
	s_nop 0
	v_add_f32_e32 v137, v144, v145
	s_waitcnt lgkmcnt(4)
	v_mul_f32_e32 v145, v148, v151
	v_mov_b32_e32 v144, v56
	v_pk_mul_f32 v[144:145], v[144:145], v[146:147]
	s_nop 0
	v_add_f32_e32 v146, v144, v145
	s_waitcnt lgkmcnt(3)
	v_mul_f32_e32 v145, v148, v158
	v_mov_b32_e32 v144, v52
	s_waitcnt vmcnt(0)
	v_pk_mul_f32 v[144:145], v[144:145], v[152:153]
	s_nop 0
	v_add_f32_e32 v147, v144, v145
	s_waitcnt lgkmcnt(2)
	v_mul_f32_e32 v145, v148, v159
	v_mov_b32_e32 v144, v48
	v_pk_mul_f32 v[144:145], v[144:145], v[154:155]
	global_load_dwordx4 v[152:155], v[140:141], off offset:256
	global_load_dwordx4 v[156:159], v[138:139], off offset:16
	v_add_f32_e32 v151, v144, v145
	v_mad_i64_i32 v[144:145], s[24:25], v134, s13, v[128:129]
	v_mul_f32_e32 v134, 0x3e38aa3b, v137
	v_mul_f32_e32 v137, 0x3e38aa3b, v146
	v_cvt_pk_bf16_f32 v146, v134, v137
	ds_bpermute_b32 v137, v150, v61
	v_mul_f32_e32 v147, 0x3e38aa3b, v147
	v_mul_f32_e32 v151, 0x3e38aa3b, v151
	v_cvt_pk_bf16_f32 v147, v147, v151
	ds_bpermute_b32 v151, v150, v57
	s_waitcnt lgkmcnt(1)
	v_mul_f32_e32 v161, v148, v137
	v_add_u32_e32 v134, 0x41, v149
	global_store_dwordx2 v[144:145], v[146:147], off nt
	s_waitcnt vmcnt(2)
	v_pk_mul_f32 v[152:153], v[160:161], v[152:153]
	s_nop 0
	v_add_f32_e32 v137, v152, v153
	s_waitcnt lgkmcnt(0)
	v_mul_f32_e32 v153, v148, v151
	v_mov_b32_e32 v152, v57
	v_pk_mul_f32 v[152:153], v[152:153], v[154:155]
	s_nop 0
	v_add_f32_e32 v151, v152, v153
	v_mul_f32_e32 v153, v148, v162
	v_mov_b32_e32 v152, v53
	s_waitcnt vmcnt(1)
	v_pk_mul_f32 v[152:153], v[152:153], v[156:157]
	s_nop 0
	v_add_f32_e32 v154, v152, v153
	v_mul_f32_e32 v153, v148, v163
	v_mov_b32_e32 v152, v49
	v_pk_mul_f32 v[144:145], v[152:153], v[158:159]
	v_mul_f32_e32 v147, 0x3e38aa3b, v154
	v_add_f32_e32 v146, v144, v145
	v_mad_i64_i32 v[144:145], s[24:25], v134, s13, v[128:129]
	v_mul_f32_e32 v134, 0x3e38aa3b, v137
	v_mul_f32_e32 v137, 0x3e38aa3b, v151
	v_mul_f32_e32 v151, 0x3e38aa3b, v146
	v_cvt_pk_bf16_f32 v146, v134, v137
	v_cvt_pk_bf16_f32 v147, v147, v151
	global_store_dwordx2 v[144:145], v[146:147], off nt
	v_add_u32_e32 v137, 0x42, v149
	v_lshlrev_b32_e32 v134, 8, v137
	v_and_b32_e32 v134, 0x1e00, v134
	v_lshl_add_u64 v[144:145], v[130:131], 0, v[134:135]
	v_add_co_u32_e32 v160, vcc, s33, v144
	v_lshl_add_u64 v[152:153], v[144:145], 0, s[84:85]
	s_nop 0
	v_addc_co_u32_e32 v161, vcc, 0, v145, vcc
	v_lshl_add_u64 v[156:157], v[144:145], 0, s[26:27]
	global_load_dwordx4 v[144:147], v[160:161], off
	s_nop 0
	global_load_dwordx4 v[152:155], v[152:153], off offset:16
	ds_bpermute_b32 v134, v150, v62
	ds_bpermute_b32 v151, v150, v58
	ds_bpermute_b32 v162, v150, v54
	v_mov_b32_e32 v158, v62
	ds_bpermute_b32 v163, v150, v50
	s_waitcnt lgkmcnt(3)
	v_mul_f32_e32 v159, v148, v134
	ds_bpermute_b32 v164, v150, v55
	ds_bpermute_b32 v165, v150, v51
	s_waitcnt vmcnt(1)
	v_pk_mul_f32 v[144:145], v[158:159], v[144:145]
	s_nop 0
	v_add_f32_e32 v134, v144, v145
	s_waitcnt lgkmcnt(4)
	v_mul_f32_e32 v145, v148, v151
	v_mov_b32_e32 v144, v58
	v_pk_mul_f32 v[144:145], v[144:145], v[146:147]
	v_mul_f32_e32 v134, 0x3e38aa3b, v134
	v_add_f32_e32 v146, v144, v145
	s_waitcnt lgkmcnt(3)
	v_mul_f32_e32 v145, v148, v162
	v_mov_b32_e32 v144, v54
	s_waitcnt vmcnt(0)
	v_pk_mul_f32 v[144:145], v[144:145], v[152:153]
	v_mov_b32_e32 v162, v63
	v_add_f32_e32 v147, v144, v145
	s_waitcnt lgkmcnt(2)
	v_mul_f32_e32 v145, v148, v163
	v_mov_b32_e32 v144, v50
	v_pk_mul_f32 v[144:145], v[144:145], v[154:155]
	global_load_dwordx4 v[152:155], v[160:161], off offset:256
	s_nop 0
	global_load_dwordx4 v[156:159], v[156:157], off offset:16
	v_add_f32_e32 v151, v144, v145
	v_mad_i64_i32 v[144:145], s[24:25], v137, s13, v[128:129]
	v_mul_f32_e32 v137, 0x3e38aa3b, v146
	v_cvt_pk_bf16_f32 v146, v134, v137
	ds_bpermute_b32 v137, v150, v63
	v_mul_f32_e32 v147, 0x3e38aa3b, v147
	v_mul_f32_e32 v151, 0x3e38aa3b, v151
	v_cvt_pk_bf16_f32 v147, v147, v151
	ds_bpermute_b32 v151, v150, v59
	s_waitcnt lgkmcnt(1)
	v_mul_f32_e32 v163, v148, v137
	v_add_u32_e32 v134, 0x43, v149
	global_store_dwordx2 v[144:145], v[146:147], off nt
	s_waitcnt vmcnt(2)
	v_pk_mul_f32 v[152:153], v[162:163], v[152:153]
	s_nop 0
	v_add_f32_e32 v137, v152, v153
	s_waitcnt lgkmcnt(0)
	v_mul_f32_e32 v153, v148, v151
	v_mov_b32_e32 v152, v59
	v_pk_mul_f32 v[152:153], v[152:153], v[154:155]
	s_nop 0
	v_add_f32_e32 v151, v152, v153
	v_mul_f32_e32 v153, v148, v164
	v_mov_b32_e32 v152, v55
	s_waitcnt vmcnt(1)
	v_pk_mul_f32 v[152:153], v[152:153], v[156:157]
	s_nop 0
	v_add_f32_e32 v154, v152, v153
	v_mul_f32_e32 v153, v148, v165
	v_mov_b32_e32 v152, v51
	v_pk_mul_f32 v[144:145], v[152:153], v[158:159]
	v_mul_f32_e32 v147, 0x3e38aa3b, v154
	v_add_f32_e32 v146, v144, v145
	v_mad_i64_i32 v[144:145], s[24:25], v134, s13, v[128:129]
	v_mul_f32_e32 v134, 0x3e38aa3b, v137
	v_mul_f32_e32 v137, 0x3e38aa3b, v151
	v_mul_f32_e32 v151, 0x3e38aa3b, v146
	v_cvt_pk_bf16_f32 v146, v134, v137
	v_cvt_pk_bf16_f32 v147, v147, v151
	global_store_dwordx2 v[144:145], v[146:147], off nt
	v_add_u32_e32 v137, 0x50, v149
	v_lshlrev_b32_e32 v134, 8, v137
	v_and_b32_e32 v134, 0x1c00, v134
	v_lshl_add_u64 v[144:145], v[130:131], 0, v[134:135]
	v_add_co_u32_e32 v160, vcc, s33, v144
	v_lshl_add_u64 v[152:153], v[144:145], 0, s[84:85]
	s_nop 0
	v_addc_co_u32_e32 v161, vcc, 0, v145, vcc
	v_lshl_add_u64 v[156:157], v[144:145], 0, s[26:27]
	global_load_dwordx4 v[144:147], v[160:161], off
	s_nop 0
	global_load_dwordx4 v[152:155], v[152:153], off offset:16
	ds_bpermute_b32 v134, v150, v44
	ds_bpermute_b32 v151, v150, v40
	ds_bpermute_b32 v162, v150, v36
	v_mov_b32_e32 v158, v44
	ds_bpermute_b32 v163, v150, v32
	s_waitcnt lgkmcnt(3)
	v_mul_f32_e32 v159, v148, v134
	ds_bpermute_b32 v164, v150, v37
	ds_bpermute_b32 v165, v150, v33
	s_waitcnt vmcnt(1)
	v_pk_mul_f32 v[144:145], v[158:159], v[144:145]
	s_nop 0
	v_add_f32_e32 v134, v144, v145
	s_waitcnt lgkmcnt(4)
	v_mul_f32_e32 v145, v148, v151
	v_mov_b32_e32 v144, v40
	v_pk_mul_f32 v[144:145], v[144:145], v[146:147]
	v_mul_f32_e32 v134, 0x3e38aa3b, v134
	v_add_f32_e32 v146, v144, v145
	s_waitcnt lgkmcnt(3)
	v_mul_f32_e32 v145, v148, v162
	v_mov_b32_e32 v144, v36
	s_waitcnt vmcnt(0)
	v_pk_mul_f32 v[144:145], v[144:145], v[152:153]
	v_mov_b32_e32 v162, v45
	v_add_f32_e32 v147, v144, v145
	s_waitcnt lgkmcnt(2)
	v_mul_f32_e32 v145, v148, v163
	v_mov_b32_e32 v144, v32
	v_pk_mul_f32 v[144:145], v[144:145], v[154:155]
	global_load_dwordx4 v[152:155], v[160:161], off offset:256
	s_nop 0
	global_load_dwordx4 v[156:159], v[156:157], off offset:16
	v_add_f32_e32 v151, v144, v145
	v_mad_i64_i32 v[144:145], s[24:25], v137, s13, v[128:129]
	v_mul_f32_e32 v137, 0x3e38aa3b, v146
	v_cvt_pk_bf16_f32 v146, v134, v137
	ds_bpermute_b32 v137, v150, v45
	v_mul_f32_e32 v147, 0x3e38aa3b, v147
	v_mul_f32_e32 v151, 0x3e38aa3b, v151
	v_cvt_pk_bf16_f32 v147, v147, v151
	ds_bpermute_b32 v151, v150, v41
	s_waitcnt lgkmcnt(1)
	v_mul_f32_e32 v163, v148, v137
	v_add_u32_e32 v134, 0x51, v149
	global_store_dwordx2 v[144:145], v[146:147], off nt
	s_waitcnt vmcnt(2)
	v_pk_mul_f32 v[152:153], v[162:163], v[152:153]
	s_nop 0
	v_add_f32_e32 v137, v152, v153
	s_waitcnt lgkmcnt(0)
	v_mul_f32_e32 v153, v148, v151
	v_mov_b32_e32 v152, v41
	v_pk_mul_f32 v[152:153], v[152:153], v[154:155]
	s_nop 0
	v_add_f32_e32 v151, v152, v153
	v_mul_f32_e32 v153, v148, v164
	v_mov_b32_e32 v152, v37
	s_waitcnt vmcnt(1)
	v_pk_mul_f32 v[152:153], v[152:153], v[156:157]
	s_nop 0
	v_add_f32_e32 v154, v152, v153
	v_mul_f32_e32 v153, v148, v165
	v_mov_b32_e32 v152, v33
	v_pk_mul_f32 v[144:145], v[152:153], v[158:159]
	v_mul_f32_e32 v147, 0x3e38aa3b, v154
	v_add_f32_e32 v146, v144, v145
	v_mad_i64_i32 v[144:145], s[24:25], v134, s13, v[128:129]
	v_mul_f32_e32 v134, 0x3e38aa3b, v137
	v_mul_f32_e32 v137, 0x3e38aa3b, v151
	v_mul_f32_e32 v151, 0x3e38aa3b, v146
	v_cvt_pk_bf16_f32 v146, v134, v137
	v_cvt_pk_bf16_f32 v147, v147, v151
	global_store_dwordx2 v[144:145], v[146:147], off nt
	v_add_u32_e32 v137, 0x52, v149
	v_lshlrev_b32_e32 v134, 8, v137
	v_and_b32_e32 v134, 0x1e00, v134
	v_lshl_add_u64 v[144:145], v[130:131], 0, v[134:135]
	v_add_co_u32_e32 v160, vcc, s33, v144
	v_lshl_add_u64 v[152:153], v[144:145], 0, s[84:85]
	s_nop 0
	v_addc_co_u32_e32 v161, vcc, 0, v145, vcc
	v_lshl_add_u64 v[156:157], v[144:145], 0, s[26:27]
	global_load_dwordx4 v[144:147], v[160:161], off
	s_nop 0
	global_load_dwordx4 v[152:155], v[152:153], off offset:16
	ds_bpermute_b32 v134, v150, v46
	ds_bpermute_b32 v151, v150, v42
	ds_bpermute_b32 v162, v150, v38
	v_mov_b32_e32 v158, v46
	ds_bpermute_b32 v163, v150, v34
	s_waitcnt lgkmcnt(3)
	v_mul_f32_e32 v159, v148, v134
	ds_bpermute_b32 v164, v150, v39
	ds_bpermute_b32 v165, v150, v35
	s_waitcnt vmcnt(1)
	v_pk_mul_f32 v[144:145], v[158:159], v[144:145]
	s_nop 0
	v_add_f32_e32 v134, v144, v145
	s_waitcnt lgkmcnt(4)
	v_mul_f32_e32 v145, v148, v151
	v_mov_b32_e32 v144, v42
	v_pk_mul_f32 v[144:145], v[144:145], v[146:147]
	v_mul_f32_e32 v134, 0x3e38aa3b, v134
	v_add_f32_e32 v146, v144, v145
	s_waitcnt lgkmcnt(3)
	v_mul_f32_e32 v145, v148, v162
	v_mov_b32_e32 v144, v38
	s_waitcnt vmcnt(0)
	v_pk_mul_f32 v[144:145], v[144:145], v[152:153]
	v_mov_b32_e32 v162, v47
	v_add_f32_e32 v147, v144, v145
	s_waitcnt lgkmcnt(2)
	v_mul_f32_e32 v145, v148, v163
	v_mov_b32_e32 v144, v34
	v_pk_mul_f32 v[144:145], v[144:145], v[154:155]
	global_load_dwordx4 v[152:155], v[160:161], off offset:256
	s_nop 0
	global_load_dwordx4 v[156:159], v[156:157], off offset:16
	v_add_f32_e32 v151, v144, v145
	v_mad_i64_i32 v[144:145], s[24:25], v137, s13, v[128:129]
	v_mul_f32_e32 v137, 0x3e38aa3b, v146
	v_cvt_pk_bf16_f32 v146, v134, v137
	ds_bpermute_b32 v137, v150, v47
	v_mul_f32_e32 v147, 0x3e38aa3b, v147
	v_mul_f32_e32 v151, 0x3e38aa3b, v151
	v_cvt_pk_bf16_f32 v147, v147, v151
	ds_bpermute_b32 v151, v150, v43
	s_waitcnt lgkmcnt(1)
	v_mul_f32_e32 v163, v148, v137
	v_add_u32_e32 v134, 0x53, v149
	global_store_dwordx2 v[144:145], v[146:147], off nt
	s_waitcnt vmcnt(2)
	v_pk_mul_f32 v[152:153], v[162:163], v[152:153]
	s_nop 0
	v_add_f32_e32 v137, v152, v153
	s_waitcnt lgkmcnt(0)
	v_mul_f32_e32 v153, v148, v151
	v_mov_b32_e32 v152, v43
	v_pk_mul_f32 v[152:153], v[152:153], v[154:155]
	s_nop 0
	v_add_f32_e32 v151, v152, v153
	v_mul_f32_e32 v153, v148, v164
	v_mov_b32_e32 v152, v39
	s_waitcnt vmcnt(1)
	v_pk_mul_f32 v[152:153], v[152:153], v[156:157]
	s_nop 0
	v_add_f32_e32 v154, v152, v153
	v_mul_f32_e32 v153, v148, v165
	v_mov_b32_e32 v152, v35
	v_pk_mul_f32 v[144:145], v[152:153], v[158:159]
	v_mul_f32_e32 v147, 0x3e38aa3b, v154
	v_add_f32_e32 v146, v144, v145
	v_mad_i64_i32 v[144:145], s[24:25], v134, s13, v[128:129]
	v_mul_f32_e32 v134, 0x3e38aa3b, v137
	v_mul_f32_e32 v137, 0x3e38aa3b, v151
	v_mul_f32_e32 v151, 0x3e38aa3b, v146
	v_cvt_pk_bf16_f32 v146, v134, v137
	v_cvt_pk_bf16_f32 v147, v147, v151
	global_store_dwordx2 v[144:145], v[146:147], off nt
	v_add_u32_e32 v134, 0x60, v149
	global_load_dwordx4 v[144:147], v[140:141], off
	global_load_dwordx4 v[152:155], v[142:143], off offset:16
	ds_bpermute_b32 v137, v150, v28
	ds_bpermute_b32 v151, v150, v24
	ds_bpermute_b32 v158, v150, v20
	v_mov_b32_e32 v156, v28
	ds_bpermute_b32 v159, v150, v16
	s_waitcnt lgkmcnt(3)
	v_mul_f32_e32 v157, v148, v137
	s_waitcnt vmcnt(1)
	v_pk_mul_f32 v[142:143], v[156:157], v[144:145]
	s_nop 0
	v_add_f32_e32 v137, v142, v143
	s_waitcnt lgkmcnt(2)
	v_mul_f32_e32 v143, v148, v151
	v_mov_b32_e32 v142, v24
	v_pk_mul_f32 v[142:143], v[142:143], v[146:147]
	ds_bpermute_b32 v151, v150, v25
	v_add_f32_e32 v144, v142, v143
	s_waitcnt lgkmcnt(2)
	v_mul_f32_e32 v143, v148, v158
	v_mov_b32_e32 v142, v20
	s_waitcnt vmcnt(0)
	v_pk_mul_f32 v[142:143], v[142:143], v[152:153]
	ds_bpermute_b32 v156, v150, v21
	v_add_f32_e32 v145, v142, v143
	s_waitcnt lgkmcnt(2)
	v_mul_f32_e32 v143, v148, v159
	v_mov_b32_e32 v142, v16
	v_pk_mul_f32 v[142:143], v[142:143], v[154:155]
	global_load_dwordx4 v[152:155], v[140:141], off offset:256
	s_nop 0
	global_load_dwordx4 v[138:141], v[138:139], off offset:16
	v_add_f32_e32 v146, v142, v143
	v_mad_i64_i32 v[142:143], s[24:25], v134, s13, v[128:129]
	v_mul_f32_e32 v134, 0x3e38aa3b, v137
	v_mul_f32_e32 v137, 0x3e38aa3b, v144
	v_cvt_pk_bf16_f32 v144, v134, v137
	ds_bpermute_b32 v137, v150, v29
	v_mul_f32_e32 v145, 0x3e38aa3b, v145
	v_mul_f32_e32 v146, 0x3e38aa3b, v146
	v_cvt_pk_bf16_f32 v145, v145, v146
	v_mov_b32_e32 v146, v29
	s_waitcnt lgkmcnt(0)
	v_mul_f32_e32 v147, v148, v137
	ds_bpermute_b32 v157, v150, v17
	v_add_u32_e32 v134, 0x61, v149
	global_store_dwordx2 v[142:143], v[144:145], off nt
	s_waitcnt vmcnt(2)
	v_pk_mul_f32 v[146:147], v[146:147], v[152:153]
	s_nop 0
	v_add_f32_e32 v137, v146, v147
	v_mul_f32_e32 v147, v148, v151
	v_mov_b32_e32 v146, v25
	v_pk_mul_f32 v[146:147], v[146:147], v[154:155]
	s_nop 0
	v_add_f32_e32 v151, v146, v147
	v_mul_f32_e32 v147, v148, v156
	v_mov_b32_e32 v146, v21
	s_waitcnt vmcnt(1)
	v_pk_mul_f32 v[138:139], v[146:147], v[138:139]
	s_nop 0
	v_add_f32_e32 v146, v138, v139
	s_waitcnt lgkmcnt(0)
	v_mul_f32_e32 v139, v148, v157
	v_mov_b32_e32 v138, v17
	v_pk_mul_f32 v[138:139], v[138:139], v[140:141]
	v_mul_f32_e32 v141, 0x3e38aa3b, v146
	v_add_f32_e32 v140, v138, v139
	v_mad_i64_i32 v[138:139], s[24:25], v134, s13, v[128:129]
	v_mul_f32_e32 v134, 0x3e38aa3b, v137
	v_mul_f32_e32 v137, 0x3e38aa3b, v151
	v_mul_f32_e32 v142, 0x3e38aa3b, v140
	v_cvt_pk_bf16_f32 v140, v134, v137
	v_cvt_pk_bf16_f32 v141, v141, v142
	global_store_dwordx2 v[138:139], v[140:141], off nt
	v_add_u32_e32 v137, 0x62, v149
	v_lshlrev_b32_e32 v134, 8, v137
	v_and_b32_e32 v134, 0x1e00, v134
	v_lshl_add_u64 v[138:139], v[130:131], 0, v[134:135]
	v_add_co_u32_e32 v154, vcc, s33, v138
	v_lshl_add_u64 v[142:143], v[138:139], 0, s[84:85]
	s_nop 0
	v_addc_co_u32_e32 v155, vcc, 0, v139, vcc
	v_lshl_add_u64 v[146:147], v[138:139], 0, s[26:27]
	global_load_dwordx4 v[138:141], v[154:155], off
	s_nop 0
	global_load_dwordx4 v[142:145], v[142:143], off offset:16
	ds_bpermute_b32 v134, v150, v30
	ds_bpermute_b32 v151, v150, v26
	ds_bpermute_b32 v156, v150, v22
	v_mov_b32_e32 v152, v30
	ds_bpermute_b32 v157, v150, v18
	s_waitcnt lgkmcnt(3)
	v_mul_f32_e32 v153, v148, v134
	ds_bpermute_b32 v158, v150, v23
	ds_bpermute_b32 v159, v150, v19
	s_waitcnt vmcnt(1)
	v_pk_mul_f32 v[138:139], v[152:153], v[138:139]
	s_nop 0
	v_add_f32_e32 v134, v138, v139
	s_waitcnt lgkmcnt(4)
	v_mul_f32_e32 v139, v148, v151
	v_mov_b32_e32 v138, v26
	v_pk_mul_f32 v[138:139], v[138:139], v[140:141]
	v_mul_f32_e32 v134, 0x3e38aa3b, v134
	v_add_f32_e32 v140, v138, v139
	s_waitcnt lgkmcnt(3)
	v_mul_f32_e32 v139, v148, v156
	v_mov_b32_e32 v138, v22
	s_waitcnt vmcnt(0)
	v_pk_mul_f32 v[138:139], v[138:139], v[142:143]
	ds_bpermute_b32 v151, v150, v27
	v_add_f32_e32 v141, v138, v139
	s_waitcnt lgkmcnt(3)
	v_mul_f32_e32 v139, v148, v157
	v_mov_b32_e32 v138, v18
	v_pk_mul_f32 v[138:139], v[138:139], v[144:145]
	v_mul_f32_e32 v141, 0x3e38aa3b, v141
	v_add_f32_e32 v142, v138, v139
	v_mul_f32_e32 v142, 0x3e38aa3b, v142
	v_cvt_pk_bf16_f32 v141, v141, v142
	global_load_dwordx4 v[142:145], v[154:155], off offset:256
	s_nop 0
	global_load_dwordx4 v[152:155], v[146:147], off offset:16
	v_mad_i64_i32 v[138:139], s[24:25], v137, s13, v[128:129]
	v_mul_f32_e32 v137, 0x3e38aa3b, v140
	v_cvt_pk_bf16_f32 v140, v134, v137
	ds_bpermute_b32 v137, v150, v31
	v_mov_b32_e32 v156, v31
	v_add_u32_e32 v134, 0x63, v149
	global_store_dwordx2 v[138:139], v[140:141], off nt
	s_waitcnt lgkmcnt(0)
	v_mul_f32_e32 v157, v148, v137
	s_waitcnt vmcnt(2)
	v_pk_mul_f32 v[142:143], v[156:157], v[142:143]
	s_nop 0
	v_add_f32_e32 v137, v142, v143
	v_mul_f32_e32 v143, v148, v151
	v_mov_b32_e32 v142, v27
	v_pk_mul_f32 v[142:143], v[142:143], v[144:145]
	s_nop 0
	v_add_f32_e32 v144, v142, v143
	v_mul_f32_e32 v143, v148, v158
	v_mov_b32_e32 v142, v23
	s_waitcnt vmcnt(1)
	v_pk_mul_f32 v[142:143], v[142:143], v[152:153]
	s_nop 0
	v_add_f32_e32 v145, v142, v143
	v_mul_f32_e32 v143, v148, v159
	v_mov_b32_e32 v142, v19
	v_pk_mul_f32 v[138:139], v[142:143], v[154:155]
	v_mul_f32_e32 v141, 0x3e38aa3b, v145
	v_add_f32_e32 v140, v138, v139
	v_mad_i64_i32 v[138:139], s[24:25], v134, s13, v[128:129]
	v_mul_f32_e32 v134, 0x3e38aa3b, v137
	v_mul_f32_e32 v137, 0x3e38aa3b, v144
	v_mul_f32_e32 v142, 0x3e38aa3b, v140
	v_cvt_pk_bf16_f32 v140, v134, v137
	v_cvt_pk_bf16_f32 v141, v141, v142
	global_store_dwordx2 v[138:139], v[140:141], off nt
	v_add_u32_e32 v137, 0x70, v149
	v_lshlrev_b32_e32 v134, 8, v137
	v_and_b32_e32 v134, 0x1c00, v134
	v_lshl_add_u64 v[138:139], v[130:131], 0, v[134:135]
	v_add_co_u32_e32 v154, vcc, s33, v138
	v_lshl_add_u64 v[142:143], v[138:139], 0, s[84:85]
	s_nop 0
	v_addc_co_u32_e32 v155, vcc, 0, v139, vcc
	v_lshl_add_u64 v[146:147], v[138:139], 0, s[26:27]
	global_load_dwordx4 v[138:141], v[154:155], off
	s_nop 0
	global_load_dwordx4 v[142:145], v[142:143], off offset:16
	ds_bpermute_b32 v134, v150, v12
	ds_bpermute_b32 v151, v150, v8
	ds_bpermute_b32 v156, v150, v4
	v_mov_b32_e32 v152, v12
	ds_bpermute_b32 v157, v150, v0
	s_waitcnt lgkmcnt(3)
	v_mul_f32_e32 v153, v148, v134
	ds_bpermute_b32 v158, v150, v5
	ds_bpermute_b32 v159, v150, v1
	s_waitcnt vmcnt(1)
	v_pk_mul_f32 v[138:139], v[152:153], v[138:139]
	s_nop 0
	v_add_f32_e32 v134, v138, v139
	s_waitcnt lgkmcnt(4)
	v_mul_f32_e32 v139, v148, v151
	v_mov_b32_e32 v138, v8
	v_pk_mul_f32 v[138:139], v[138:139], v[140:141]
	v_mul_f32_e32 v134, 0x3e38aa3b, v134
	v_add_f32_e32 v140, v138, v139
	s_waitcnt lgkmcnt(3)
	v_mul_f32_e32 v139, v148, v156
	v_mov_b32_e32 v138, v4
	s_waitcnt vmcnt(0)
	v_pk_mul_f32 v[138:139], v[138:139], v[142:143]
	ds_bpermute_b32 v151, v150, v9
	v_add_f32_e32 v141, v138, v139
	s_waitcnt lgkmcnt(3)
	v_mul_f32_e32 v139, v148, v157
	v_mov_b32_e32 v138, v0
	v_pk_mul_f32 v[138:139], v[138:139], v[144:145]
	v_mul_f32_e32 v141, 0x3e38aa3b, v141
	v_add_f32_e32 v142, v138, v139
	v_mul_f32_e32 v142, 0x3e38aa3b, v142
	v_cvt_pk_bf16_f32 v141, v141, v142
	global_load_dwordx4 v[142:145], v[154:155], off offset:256
	s_nop 0
	global_load_dwordx4 v[152:155], v[146:147], off offset:16
	v_mad_i64_i32 v[138:139], s[24:25], v137, s13, v[128:129]
	v_mul_f32_e32 v137, 0x3e38aa3b, v140
	v_cvt_pk_bf16_f32 v140, v134, v137
	ds_bpermute_b32 v137, v150, v13
	v_mov_b32_e32 v156, v13
	v_add_u32_e32 v134, 0x71, v149
	global_store_dwordx2 v[138:139], v[140:141], off nt
	s_waitcnt lgkmcnt(0)
	v_mul_f32_e32 v157, v148, v137
	s_waitcnt vmcnt(2)
	v_pk_mul_f32 v[142:143], v[156:157], v[142:143]
	s_nop 0
	v_add_f32_e32 v137, v142, v143
	v_mul_f32_e32 v143, v148, v151
	v_mov_b32_e32 v142, v9
	v_pk_mul_f32 v[142:143], v[142:143], v[144:145]
	s_nop 0
	v_add_f32_e32 v144, v142, v143
	v_mul_f32_e32 v143, v148, v158
	v_mov_b32_e32 v142, v5
	s_waitcnt vmcnt(1)
	v_pk_mul_f32 v[142:143], v[142:143], v[152:153]
	s_nop 0
	v_add_f32_e32 v145, v142, v143
	v_mul_f32_e32 v143, v148, v159
	v_mov_b32_e32 v142, v1
	v_pk_mul_f32 v[138:139], v[142:143], v[154:155]
	v_mul_f32_e32 v141, 0x3e38aa3b, v145
	v_add_f32_e32 v140, v138, v139
	v_mad_i64_i32 v[138:139], s[24:25], v134, s13, v[128:129]
	v_mul_f32_e32 v134, 0x3e38aa3b, v137
	v_mul_f32_e32 v137, 0x3e38aa3b, v144
	v_mul_f32_e32 v142, 0x3e38aa3b, v140
	v_cvt_pk_bf16_f32 v140, v134, v137
	v_cvt_pk_bf16_f32 v141, v141, v142
	global_store_dwordx2 v[138:139], v[140:141], off nt
	v_add_u32_e32 v137, 0x72, v149
	v_lshlrev_b32_e32 v134, 8, v137
	v_and_b32_e32 v134, 0x1e00, v134
	v_lshl_add_u64 v[130:131], v[130:131], 0, v[134:135]
	v_add_co_u32_e32 v154, vcc, s33, v130
	v_lshl_add_u64 v[142:143], v[130:131], 0, s[84:85]
	s_nop 0
	v_addc_co_u32_e32 v155, vcc, 0, v131, vcc
	global_load_dwordx4 v[138:141], v[154:155], off
	s_nop 0
	global_load_dwordx4 v[142:145], v[142:143], off offset:16
	ds_bpermute_b32 v134, v150, v14
	ds_bpermute_b32 v151, v150, v10
	ds_bpermute_b32 v156, v150, v6
	v_mov_b32_e32 v152, v14
	v_lshl_add_u64 v[146:147], v[130:131], 0, s[26:27]
	s_waitcnt lgkmcnt(2)
	v_mul_f32_e32 v153, v148, v134
	ds_bpermute_b32 v157, v150, v2
	s_waitcnt vmcnt(1)
	v_pk_mul_f32 v[130:131], v[152:153], v[138:139]
	s_nop 0
	v_add_f32_e32 v134, v130, v131
	s_waitcnt lgkmcnt(2)
	v_mul_f32_e32 v131, v148, v151
	v_mov_b32_e32 v130, v10
	v_pk_mul_f32 v[130:131], v[130:131], v[140:141]
	v_mul_f32_e32 v134, 0x3e38aa3b, v134
	v_add_f32_e32 v138, v130, v131
	s_waitcnt lgkmcnt(1)
	v_mul_f32_e32 v131, v148, v156
	v_mov_b32_e32 v130, v6
	s_waitcnt vmcnt(0)
	v_pk_mul_f32 v[130:131], v[130:131], v[142:143]
	ds_bpermute_b32 v152, v150, v7
	v_add_f32_e32 v139, v130, v131
	s_waitcnt lgkmcnt(1)
	v_mul_f32_e32 v131, v148, v157
	v_mov_b32_e32 v130, v2
	v_pk_mul_f32 v[130:131], v[130:131], v[144:145]
	v_mul_f32_e32 v139, 0x3e38aa3b, v139
	v_add_f32_e32 v140, v130, v131
	v_mul_f32_e32 v140, 0x3e38aa3b, v140
	v_cvt_pk_bf16_f32 v139, v139, v140
	global_load_dwordx4 v[140:143], v[154:155], off offset:256
	s_nop 0
	global_load_dwordx4 v[144:147], v[146:147], off offset:16
	v_mad_i64_i32 v[130:131], s[24:25], v137, s13, v[128:129]
	v_mul_f32_e32 v137, 0x3e38aa3b, v138
	v_cvt_pk_bf16_f32 v138, v134, v137
	ds_bpermute_b32 v137, v150, v15
	v_add_u32_e32 v134, 0x73, v149
	ds_bpermute_b32 v149, v150, v11
	ds_bpermute_b32 v153, v150, v3
	v_mov_b32_e32 v150, v15
	s_waitcnt lgkmcnt(2)
	v_mul_f32_e32 v151, v148, v137
	global_store_dwordx2 v[130:131], v[138:139], off nt
	s_waitcnt vmcnt(2)
	v_pk_mul_f32 v[140:141], v[150:151], v[140:141]
	s_nop 0
	v_add_f32_e32 v137, v140, v141
	s_waitcnt lgkmcnt(1)
	v_mul_f32_e32 v141, v148, v149
	v_mov_b32_e32 v140, v11
	v_pk_mul_f32 v[140:141], v[140:141], v[142:143]
	s_nop 0
	v_add_f32_e32 v142, v140, v141
	v_mul_f32_e32 v141, v148, v152
	v_mov_b32_e32 v140, v7
	s_waitcnt vmcnt(1)
	v_pk_mul_f32 v[140:141], v[140:141], v[144:145]
	s_nop 0
	v_add_f32_e32 v143, v140, v141
	s_waitcnt lgkmcnt(0)
	v_mul_f32_e32 v141, v148, v153
	v_mov_b32_e32 v140, v3
	v_pk_mul_f32 v[130:131], v[140:141], v[146:147]
	v_mad_i64_i32 v[128:129], s[24:25], v134, s13, v[128:129]
	v_add_f32_e32 v130, v130, v131
	v_mul_f32_e32 v131, 0x3e38aa3b, v137
	s_xor_b64 s[74:75], exec, -1
	v_mul_f32_e32 v134, 0x3e38aa3b, v142
	v_mul_f32_e32 v137, 0x3e38aa3b, v143
	v_mul_f32_e32 v138, 0x3e38aa3b, v130
	v_cvt_pk_bf16_f32 v130, v131, v134
	v_cvt_pk_bf16_f32 v131, v137, v138
	global_store_dwordx2 v[128:129], v[130:131], off

.LBB0_492:
	s_or_saveexec_b64 s[8:9], s[8:9]
	s_mov_b64 s[68:69], 0
	s_xor_b64 exec, exec, s[8:9]
	s_cbranch_execz .LBB0_500
	v_cmp_lt_i32_e32 vcc, 1, v176
	s_mov_b64 s[72:73], 0
	s_mov_b64 s[68:69], -1
	s_mov_b64 s[74:75], s[66:67]
	s_and_saveexec_b64 s[0:1], vcc
	s_cbranch_execz .LBB0_499
	v_cmp_lt_i32_e32 vcc, 2, v176
	s_mov_b64 s[72:73], -1
	s_mov_b64 s[74:75], s[66:67]
	s_and_saveexec_b64 s[68:69], vcc
	s_cbranch_execz .LBB0_498
	v_cmp_lt_i32_e32 vcc, 3, v176
	s_mov_b64 s[74:75], -1
	s_and_saveexec_b64 s[72:73], vcc
	s_cbranch_execz .LBB0_497
	v_mbcnt_hi_u32_b32 v128, -1, v204
	v_and_b32_e32 v130, 64, v128
	v_xor_b32_e32 v129, 8, v128
	v_add_u32_e32 v130, 64, v130
	v_cmp_lt_i32_e32 vcc, v129, v130
	v_readlane_b32 s36, v253, 44
	v_ashrrev_i32_e32 v137, 31, v136
	v_cndmask_b32_e32 v128, v128, v129, vcc
	v_cmp_gt_u32_e32 vcc, 8, v175
	v_readlane_b32 s37, v253, 45
	v_lshl_add_u32 v148, v146, 2, v211
	v_lshlrev_b32_e32 v149, 2, v128
	v_cndmask_b32_e64 v147, 1.0, -1.0, vcc
	v_readlane_b32 s38, v253, 46
	v_readlane_b32 s39, v253, 47
	v_readlane_b32 s40, v253, 48
	v_readlane_b32 s41, v253, 49
	v_readlane_b32 s42, v253, 50
	v_readlane_b32 s43, v253, 51
	v_readlane_b32 s44, v253, 52
	v_readlane_b32 s45, v253, 53
	v_readlane_b32 s46, v253, 54
	v_readlane_b32 s47, v253, 55
	v_readlane_b32 s48, v253, 56
	v_readlane_b32 s49, v253, 57
	v_readlane_b32 s50, v253, 58
	v_readlane_b32 s51, v253, 59
	v_lshl_add_u64 v[138:139], v[136:137], 1, s[36:37]
	v_lshlrev_b32_e32 v128, 5, v210
	v_and_b32_e32 v134, 0xe0, v128
	v_lshlrev_b32_e32 v128, 8, v148
	v_lshl_add_u64 v[140:141], s[58:59], 0, v[134:135]
	v_and_b32_e32 v134, 0x7fc00, v128
	ds_bpermute_b32 v128, v149, v124
	v_lshl_add_u64 v[150:151], v[140:141], 0, v[134:135]
	ds_bpermute_b32 v134, v149, v120
	ds_bpermute_b32 v137, v149, v116
	v_mov_b32_e32 v152, v124
	s_waitcnt lgkmcnt(2)
	v_mul_f32_e32 v153, v147, v128
	global_load_dwordx4 v[128:131], v[150:151], off offset:16
	global_load_dwordx4 v[142:145], v[150:151], off
	ds_bpermute_b32 v154, v149, v112
	ds_bpermute_b32 v156, v149, v117
	ds_bpermute_b32 v157, v149, v113
	s_waitcnt vmcnt(0)
	v_pk_mul_f32 v[142:143], v[152:153], v[142:143]
	s_nop 0
	v_add_f32_e32 v152, v142, v143
	s_waitcnt lgkmcnt(4)
	v_mul_f32_e32 v143, v147, v134
	v_mov_b32_e32 v142, v120
	v_pk_mul_f32 v[142:143], v[142:143], v[144:145]
	s_nop 0
	v_add_f32_e32 v134, v142, v143
	s_waitcnt lgkmcnt(3)
	v_mul_f32_e32 v143, v147, v137
	v_mov_b32_e32 v142, v116
	v_pk_mul_f32 v[128:129], v[142:143], v[128:129]
	v_mad_i64_i32 v[142:143], s[24:25], v148, s13, v[138:139]
	v_add_f32_e32 v137, v128, v129
	s_waitcnt lgkmcnt(2)
	v_mul_f32_e32 v129, v147, v154
	v_mov_b32_e32 v128, v112
	v_pk_mul_f32 v[128:129], v[128:129], v[130:131]
	v_mul_f32_e32 v131, 0x3e38aa3b, v137
	v_add_f32_e32 v128, v128, v129
	v_mul_f32_e32 v128, 0x3e38aa3b, v128
	v_cvt_pk_bf16_f32 v145, v131, v128
	ds_bpermute_b32 v128, v149, v125
	v_mul_f32_e32 v129, 0x3e38aa3b, v152
	v_mul_f32_e32 v130, 0x3e38aa3b, v134
	v_cvt_pk_bf16_f32 v144, v129, v130
	ds_bpermute_b32 v137, v149, v121
	s_waitcnt lgkmcnt(1)
	v_mul_f32_e32 v155, v147, v128
	global_load_dwordx4 v[128:131], v[150:151], off offset:272
	s_nop 0
	global_load_dwordx4 v[150:153], v[150:151], off offset:256
	v_mov_b32_e32 v154, v125
	v_or_b32_e32 v134, 1, v148
	global_store_dwordx2 v[142:143], v[144:145], off nt
	s_waitcnt vmcnt(1)
	v_pk_mul_f32 v[150:151], v[154:155], v[150:151]
	s_nop 0
	v_add_f32_e32 v154, v150, v151
	s_waitcnt lgkmcnt(0)
	v_mul_f32_e32 v151, v147, v137
	v_mov_b32_e32 v150, v121
	v_pk_mul_f32 v[150:151], v[150:151], v[152:153]
	s_nop 0
	v_add_f32_e32 v137, v150, v151
	v_mul_f32_e32 v151, v147, v156
	v_mov_b32_e32 v150, v117
	v_pk_mul_f32 v[128:129], v[150:151], v[128:129]
	s_nop 0
	v_add_f32_e32 v150, v128, v129
	v_mul_f32_e32 v129, v147, v157
	v_mov_b32_e32 v128, v113
	v_pk_mul_f32 v[128:129], v[128:129], v[130:131]
	v_mul_f32_e32 v131, 0x3e38aa3b, v154
	v_add_f32_e32 v130, v128, v129
	v_mad_i64_i32 v[128:129], s[24:25], v134, s13, v[138:139]
	v_mul_f32_e32 v134, 0x3e38aa3b, v137
	v_mul_f32_e32 v137, 0x3e38aa3b, v150
	v_mul_f32_e32 v142, 0x3e38aa3b, v130
	v_cvt_pk_bf16_f32 v130, v131, v134
	v_cvt_pk_bf16_f32 v131, v137, v142
	global_store_dwordx2 v[128:129], v[130:131], off nt
	v_or_b32_e32 v137, 2, v148
	v_lshlrev_b32_e32 v128, 8, v137
	v_and_b32_e32 v134, 0x7fe00, v128
	ds_bpermute_b32 v128, v149, v126
	v_lshl_add_u64 v[150:151], v[140:141], 0, v[134:135]
	ds_bpermute_b32 v134, v149, v122
	ds_bpermute_b32 v154, v149, v118
	v_mov_b32_e32 v152, v126
	s_waitcnt lgkmcnt(2)
	v_mul_f32_e32 v153, v147, v128
	global_load_dwordx4 v[128:131], v[150:151], off offset:16
	global_load_dwordx4 v[142:145], v[150:151], off
	ds_bpermute_b32 v155, v149, v114
	ds_bpermute_b32 v156, v149, v119
	ds_bpermute_b32 v157, v149, v115
	s_waitcnt vmcnt(0)
	v_pk_mul_f32 v[142:143], v[152:153], v[142:143]
	s_nop 0
	v_add_f32_e32 v152, v142, v143
	s_waitcnt lgkmcnt(4)
	v_mul_f32_e32 v143, v147, v134
	v_mov_b32_e32 v142, v122
	v_pk_mul_f32 v[142:143], v[142:143], v[144:145]
	s_nop 0
	v_add_f32_e32 v134, v142, v143
	s_waitcnt lgkmcnt(3)
	v_mul_f32_e32 v143, v147, v154
	v_mov_b32_e32 v142, v118
	v_pk_mul_f32 v[128:129], v[142:143], v[128:129]
	v_mad_i64_i32 v[142:143], s[24:25], v137, s13, v[138:139]
	v_add_f32_e32 v144, v128, v129
	s_waitcnt lgkmcnt(2)
	v_mul_f32_e32 v129, v147, v155
	v_mov_b32_e32 v128, v114
	v_pk_mul_f32 v[128:129], v[128:129], v[130:131]
	v_mul_f32_e32 v131, 0x3e38aa3b, v144
	v_add_f32_e32 v128, v128, v129
	v_mul_f32_e32 v128, 0x3e38aa3b, v128
	v_cvt_pk_bf16_f32 v145, v131, v128
	ds_bpermute_b32 v128, v149, v127
	v_mul_f32_e32 v129, 0x3e38aa3b, v152
	v_mul_f32_e32 v130, 0x3e38aa3b, v134
	v_cvt_pk_bf16_f32 v144, v129, v130
	ds_bpermute_b32 v137, v149, v123
	s_waitcnt lgkmcnt(1)
	v_mul_f32_e32 v155, v147, v128
	global_load_dwordx4 v[128:131], v[150:151], off offset:272
	s_nop 0
	global_load_dwordx4 v[150:153], v[150:151], off offset:256
	v_mov_b32_e32 v154, v127
	v_or_b32_e32 v134, 3, v148
	global_store_dwordx2 v[142:143], v[144:145], off nt
	s_waitcnt vmcnt(1)
	v_pk_mul_f32 v[150:151], v[154:155], v[150:151]
	s_nop 0
	v_add_f32_e32 v154, v150, v151
	s_waitcnt lgkmcnt(0)
	v_mul_f32_e32 v151, v147, v137
	v_mov_b32_e32 v150, v123
	v_pk_mul_f32 v[150:151], v[150:151], v[152:153]
	s_nop 0
	v_add_f32_e32 v137, v150, v151
	v_mul_f32_e32 v151, v147, v156
	v_mov_b32_e32 v150, v119
	v_pk_mul_f32 v[128:129], v[150:151], v[128:129]
	s_nop 0
	v_add_f32_e32 v150, v128, v129
	v_mul_f32_e32 v129, v147, v157
	v_mov_b32_e32 v128, v115
	v_pk_mul_f32 v[128:129], v[128:129], v[130:131]
	v_mul_f32_e32 v131, 0x3e38aa3b, v154
	v_add_f32_e32 v130, v128, v129
	v_mad_i64_i32 v[128:129], s[24:25], v134, s13, v[138:139]
	v_mul_f32_e32 v134, 0x3e38aa3b, v137
	v_mul_f32_e32 v137, 0x3e38aa3b, v150
	v_mul_f32_e32 v142, 0x3e38aa3b, v130
	v_cvt_pk_bf16_f32 v130, v131, v134
	v_cvt_pk_bf16_f32 v131, v137, v142
	global_store_dwordx2 v[128:129], v[130:131], off nt
	v_add_u32_e32 v137, 16, v148
	v_lshlrev_b32_e32 v128, 8, v137
	v_and_b32_e32 v134, 0x7fc00, v128
	ds_bpermute_b32 v128, v149, v108
	v_lshl_add_u64 v[150:151], v[140:141], 0, v[134:135]
	ds_bpermute_b32 v134, v149, v104
	ds_bpermute_b32 v154, v149, v100
	v_mov_b32_e32 v152, v108
	s_waitcnt lgkmcnt(2)
	v_mul_f32_e32 v153, v147, v128
	global_load_dwordx4 v[128:131], v[150:151], off offset:16
	global_load_dwordx4 v[142:145], v[150:151], off
	ds_bpermute_b32 v155, v149, v96
	ds_bpermute_b32 v156, v149, v101
	ds_bpermute_b32 v157, v149, v97
	s_waitcnt vmcnt(0)
	v_pk_mul_f32 v[142:143], v[152:153], v[142:143]
	s_nop 0
	v_add_f32_e32 v152, v142, v143
	s_waitcnt lgkmcnt(4)
	v_mul_f32_e32 v143, v147, v134
	v_mov_b32_e32 v142, v104
	v_pk_mul_f32 v[142:143], v[142:143], v[144:145]
	s_nop 0
	v_add_f32_e32 v134, v142, v143
	s_waitcnt lgkmcnt(3)
	v_mul_f32_e32 v143, v147, v154
	v_mov_b32_e32 v142, v100
	v_pk_mul_f32 v[128:129], v[142:143], v[128:129]
	v_mad_i64_i32 v[142:143], s[24:25], v137, s13, v[138:139]
	v_add_f32_e32 v144, v128, v129
	s_waitcnt lgkmcnt(2)
	v_mul_f32_e32 v129, v147, v155
	v_mov_b32_e32 v128, v96
	v_pk_mul_f32 v[128:129], v[128:129], v[130:131]
	v_mul_f32_e32 v131, 0x3e38aa3b, v144
	v_add_f32_e32 v128, v128, v129
	v_mul_f32_e32 v128, 0x3e38aa3b, v128
	v_cvt_pk_bf16_f32 v145, v131, v128
	ds_bpermute_b32 v128, v149, v109
	v_mul_f32_e32 v129, 0x3e38aa3b, v152
	v_mul_f32_e32 v130, 0x3e38aa3b, v134
	v_cvt_pk_bf16_f32 v144, v129, v130
	ds_bpermute_b32 v137, v149, v105
	s_waitcnt lgkmcnt(1)
	v_mul_f32_e32 v155, v147, v128
	global_load_dwordx4 v[128:131], v[150:151], off offset:272
	s_nop 0
	global_load_dwordx4 v[150:153], v[150:151], off offset:256
	v_mov_b32_e32 v154, v109
	v_add_u32_e32 v134, 17, v148
	global_store_dwordx2 v[142:143], v[144:145], off nt
	s_waitcnt vmcnt(1)
	v_pk_mul_f32 v[150:151], v[154:155], v[150:151]
	s_nop 0
	v_add_f32_e32 v154, v150, v151
	s_waitcnt lgkmcnt(0)
	v_mul_f32_e32 v151, v147, v137
	v_mov_b32_e32 v150, v105
	v_pk_mul_f32 v[150:151], v[150:151], v[152:153]
	s_nop 0
	v_add_f32_e32 v137, v150, v151
	v_mul_f32_e32 v151, v147, v156
	v_mov_b32_e32 v150, v101
	v_pk_mul_f32 v[128:129], v[150:151], v[128:129]
	s_nop 0
	v_add_f32_e32 v150, v128, v129
	v_mul_f32_e32 v129, v147, v157
	v_mov_b32_e32 v128, v97
	v_pk_mul_f32 v[128:129], v[128:129], v[130:131]
	v_mul_f32_e32 v131, 0x3e38aa3b, v154
	v_add_f32_e32 v130, v128, v129
	v_mad_i64_i32 v[128:129], s[24:25], v134, s13, v[138:139]
	v_mul_f32_e32 v134, 0x3e38aa3b, v137
	v_mul_f32_e32 v137, 0x3e38aa3b, v150
	v_mul_f32_e32 v142, 0x3e38aa3b, v130
	v_cvt_pk_bf16_f32 v130, v131, v134
	v_cvt_pk_bf16_f32 v131, v137, v142
	global_store_dwordx2 v[128:129], v[130:131], off nt
	v_add_u32_e32 v137, 18, v148
	v_lshlrev_b32_e32 v128, 8, v137
	v_and_b32_e32 v134, 0x7fe00, v128
	ds_bpermute_b32 v128, v149, v110
	v_lshl_add_u64 v[150:151], v[140:141], 0, v[134:135]
	ds_bpermute_b32 v134, v149, v106
	ds_bpermute_b32 v154, v149, v102
	v_mov_b32_e32 v152, v110
	s_waitcnt lgkmcnt(2)
	v_mul_f32_e32 v153, v147, v128
	global_load_dwordx4 v[128:131], v[150:151], off offset:16
	global_load_dwordx4 v[142:145], v[150:151], off
	ds_bpermute_b32 v155, v149, v98
	ds_bpermute_b32 v156, v149, v103
	ds_bpermute_b32 v157, v149, v99
	s_waitcnt vmcnt(0)
	v_pk_mul_f32 v[142:143], v[152:153], v[142:143]
	s_nop 0
	v_add_f32_e32 v152, v142, v143
	s_waitcnt lgkmcnt(4)
	v_mul_f32_e32 v143, v147, v134
	v_mov_b32_e32 v142, v106
	v_pk_mul_f32 v[142:143], v[142:143], v[144:145]
	s_nop 0
	v_add_f32_e32 v134, v142, v143
	s_waitcnt lgkmcnt(3)
	v_mul_f32_e32 v143, v147, v154
	v_mov_b32_e32 v142, v102
	v_pk_mul_f32 v[128:129], v[142:143], v[128:129]
	v_mad_i64_i32 v[142:143], s[24:25], v137, s13, v[138:139]
	v_add_f32_e32 v144, v128, v129
	s_waitcnt lgkmcnt(2)
	v_mul_f32_e32 v129, v147, v155
	v_mov_b32_e32 v128, v98
	v_pk_mul_f32 v[128:129], v[128:129], v[130:131]
	v_mul_f32_e32 v131, 0x3e38aa3b, v144
	v_add_f32_e32 v128, v128, v129
	v_mul_f32_e32 v128, 0x3e38aa3b, v128
	v_cvt_pk_bf16_f32 v145, v131, v128
	ds_bpermute_b32 v128, v149, v111
	v_mul_f32_e32 v129, 0x3e38aa3b, v152
	v_mul_f32_e32 v130, 0x3e38aa3b, v134
	v_cvt_pk_bf16_f32 v144, v129, v130
	ds_bpermute_b32 v137, v149, v107
	s_waitcnt lgkmcnt(1)
	v_mul_f32_e32 v155, v147, v128
	global_load_dwordx4 v[128:131], v[150:151], off offset:272
	s_nop 0
	global_load_dwordx4 v[150:153], v[150:151], off offset:256
	v_mov_b32_e32 v154, v111
	v_add_u32_e32 v134, 19, v148
	global_store_dwordx2 v[142:143], v[144:145], off nt
	s_waitcnt vmcnt(1)
	v_pk_mul_f32 v[150:151], v[154:155], v[150:151]
	s_nop 0
	v_add_f32_e32 v154, v150, v151
	s_waitcnt lgkmcnt(0)
	v_mul_f32_e32 v151, v147, v137
	v_mov_b32_e32 v150, v107
	v_pk_mul_f32 v[150:151], v[150:151], v[152:153]
	s_nop 0
	v_add_f32_e32 v137, v150, v151
	v_mul_f32_e32 v151, v147, v156
	v_mov_b32_e32 v150, v103
	v_pk_mul_f32 v[128:129], v[150:151], v[128:129]
	s_nop 0
	v_add_f32_e32 v150, v128, v129
	v_mul_f32_e32 v129, v147, v157
	v_mov_b32_e32 v128, v99
	v_pk_mul_f32 v[128:129], v[128:129], v[130:131]
	v_mul_f32_e32 v131, 0x3e38aa3b, v154
	v_add_f32_e32 v130, v128, v129
	v_mad_i64_i32 v[128:129], s[24:25], v134, s13, v[138:139]
	v_mul_f32_e32 v134, 0x3e38aa3b, v137
	v_mul_f32_e32 v137, 0x3e38aa3b, v150
	v_mul_f32_e32 v142, 0x3e38aa3b, v130
	v_cvt_pk_bf16_f32 v130, v131, v134
	v_cvt_pk_bf16_f32 v131, v137, v142
	global_store_dwordx2 v[128:129], v[130:131], off nt
	v_add_u32_e32 v137, 32, v148
	v_lshlrev_b32_e32 v128, 8, v137
	v_and_b32_e32 v134, 0x7fc00, v128
	ds_bpermute_b32 v128, v149, v92
	v_lshl_add_u64 v[150:151], v[140:141], 0, v[134:135]
	ds_bpermute_b32 v134, v149, v88
	ds_bpermute_b32 v154, v149, v84
	v_mov_b32_e32 v152, v92
	s_waitcnt lgkmcnt(2)
	v_mul_f32_e32 v153, v147, v128
	global_load_dwordx4 v[128:131], v[150:151], off offset:16
	global_load_dwordx4 v[142:145], v[150:151], off
	ds_bpermute_b32 v155, v149, v80
	ds_bpermute_b32 v156, v149, v85
	ds_bpermute_b32 v157, v149, v81
	s_waitcnt vmcnt(0)
	v_pk_mul_f32 v[142:143], v[152:153], v[142:143]
	s_nop 0
	v_add_f32_e32 v152, v142, v143
	s_waitcnt lgkmcnt(4)
	v_mul_f32_e32 v143, v147, v134
	v_mov_b32_e32 v142, v88
	v_pk_mul_f32 v[142:143], v[142:143], v[144:145]
	s_nop 0
	v_add_f32_e32 v134, v142, v143
	s_waitcnt lgkmcnt(3)
	v_mul_f32_e32 v143, v147, v154
	v_mov_b32_e32 v142, v84
	v_pk_mul_f32 v[128:129], v[142:143], v[128:129]
	v_mad_i64_i32 v[142:143], s[24:25], v137, s13, v[138:139]
	v_add_f32_e32 v144, v128, v129
	s_waitcnt lgkmcnt(2)
	v_mul_f32_e32 v129, v147, v155
	v_mov_b32_e32 v128, v80
	v_pk_mul_f32 v[128:129], v[128:129], v[130:131]
	v_mul_f32_e32 v131, 0x3e38aa3b, v144
	v_add_f32_e32 v128, v128, v129
	v_mul_f32_e32 v128, 0x3e38aa3b, v128
	v_cvt_pk_bf16_f32 v145, v131, v128
	ds_bpermute_b32 v128, v149, v93
	v_mul_f32_e32 v129, 0x3e38aa3b, v152
	v_mul_f32_e32 v130, 0x3e38aa3b, v134
	v_cvt_pk_bf16_f32 v144, v129, v130
	ds_bpermute_b32 v137, v149, v89
	s_waitcnt lgkmcnt(1)
	v_mul_f32_e32 v155, v147, v128
	global_load_dwordx4 v[128:131], v[150:151], off offset:272
	s_nop 0
	global_load_dwordx4 v[150:153], v[150:151], off offset:256
	v_mov_b32_e32 v154, v93
	v_add_u32_e32 v134, 33, v148
	global_store_dwordx2 v[142:143], v[144:145], off nt
	s_waitcnt vmcnt(1)
	v_pk_mul_f32 v[150:151], v[154:155], v[150:151]
	s_nop 0
	v_add_f32_e32 v154, v150, v151
	s_waitcnt lgkmcnt(0)
	v_mul_f32_e32 v151, v147, v137
	v_mov_b32_e32 v150, v89
	v_pk_mul_f32 v[150:151], v[150:151], v[152:153]
	s_nop 0
	v_add_f32_e32 v137, v150, v151
	v_mul_f32_e32 v151, v147, v156
	v_mov_b32_e32 v150, v85
	v_pk_mul_f32 v[128:129], v[150:151], v[128:129]
	s_nop 0
	v_add_f32_e32 v150, v128, v129
	v_mul_f32_e32 v129, v147, v157
	v_mov_b32_e32 v128, v81
	v_pk_mul_f32 v[128:129], v[128:129], v[130:131]
	v_mul_f32_e32 v131, 0x3e38aa3b, v154
	v_add_f32_e32 v130, v128, v129
	v_mad_i64_i32 v[128:129], s[24:25], v134, s13, v[138:139]
	v_mul_f32_e32 v134, 0x3e38aa3b, v137
	v_mul_f32_e32 v137, 0x3e38aa3b, v150
	v_mul_f32_e32 v142, 0x3e38aa3b, v130
	v_cvt_pk_bf16_f32 v130, v131, v134
	v_cvt_pk_bf16_f32 v131, v137, v142
	global_store_dwordx2 v[128:129], v[130:131], off nt
	v_add_u32_e32 v137, 34, v148
	v_lshlrev_b32_e32 v128, 8, v137
	v_and_b32_e32 v134, 0x7fe00, v128
	ds_bpermute_b32 v128, v149, v94
	v_lshl_add_u64 v[150:151], v[140:141], 0, v[134:135]
	ds_bpermute_b32 v134, v149, v90
	ds_bpermute_b32 v154, v149, v86
	v_mov_b32_e32 v152, v94
	s_waitcnt lgkmcnt(2)
	v_mul_f32_e32 v153, v147, v128
	global_load_dwordx4 v[128:131], v[150:151], off offset:16
	global_load_dwordx4 v[142:145], v[150:151], off
	ds_bpermute_b32 v155, v149, v82
	ds_bpermute_b32 v156, v149, v87
	ds_bpermute_b32 v157, v149, v83
	s_waitcnt vmcnt(0)
	v_pk_mul_f32 v[142:143], v[152:153], v[142:143]
	s_nop 0
	v_add_f32_e32 v152, v142, v143
	s_waitcnt lgkmcnt(4)
	v_mul_f32_e32 v143, v147, v134
	v_mov_b32_e32 v142, v90
	v_pk_mul_f32 v[142:143], v[142:143], v[144:145]
	s_nop 0
	v_add_f32_e32 v134, v142, v143
	s_waitcnt lgkmcnt(3)
	v_mul_f32_e32 v143, v147, v154
	v_mov_b32_e32 v142, v86
	v_pk_mul_f32 v[128:129], v[142:143], v[128:129]
	v_mad_i64_i32 v[142:143], s[24:25], v137, s13, v[138:139]
	v_add_f32_e32 v144, v128, v129
	s_waitcnt lgkmcnt(2)
	v_mul_f32_e32 v129, v147, v155
	v_mov_b32_e32 v128, v82
	v_pk_mul_f32 v[128:129], v[128:129], v[130:131]
	v_mul_f32_e32 v131, 0x3e38aa3b, v144
	v_add_f32_e32 v128, v128, v129
	v_mul_f32_e32 v128, 0x3e38aa3b, v128
	v_cvt_pk_bf16_f32 v145, v131, v128
	ds_bpermute_b32 v128, v149, v95
	v_mul_f32_e32 v129, 0x3e38aa3b, v152
	v_mul_f32_e32 v130, 0x3e38aa3b, v134
	v_cvt_pk_bf16_f32 v144, v129, v130
	ds_bpermute_b32 v137, v149, v91
	s_waitcnt lgkmcnt(1)
	v_mul_f32_e32 v155, v147, v128
	global_load_dwordx4 v[128:131], v[150:151], off offset:272
	s_nop 0
	global_load_dwordx4 v[150:153], v[150:151], off offset:256
	v_mov_b32_e32 v154, v95
	v_add_u32_e32 v134, 35, v148
	global_store_dwordx2 v[142:143], v[144:145], off nt
	s_waitcnt vmcnt(1)
	v_pk_mul_f32 v[150:151], v[154:155], v[150:151]
	s_nop 0
	v_add_f32_e32 v154, v150, v151
	s_waitcnt lgkmcnt(0)
	v_mul_f32_e32 v151, v147, v137
	v_mov_b32_e32 v150, v91
	v_pk_mul_f32 v[150:151], v[150:151], v[152:153]
	s_nop 0
	v_add_f32_e32 v137, v150, v151
	v_mul_f32_e32 v151, v147, v156
	v_mov_b32_e32 v150, v87
	v_pk_mul_f32 v[128:129], v[150:151], v[128:129]
	s_nop 0
	v_add_f32_e32 v150, v128, v129
	v_mul_f32_e32 v129, v147, v157
	v_mov_b32_e32 v128, v83
	v_pk_mul_f32 v[128:129], v[128:129], v[130:131]
	v_mul_f32_e32 v131, 0x3e38aa3b, v154
	v_add_f32_e32 v130, v128, v129
	v_mad_i64_i32 v[128:129], s[24:25], v134, s13, v[138:139]
	v_mul_f32_e32 v134, 0x3e38aa3b, v137
	v_mul_f32_e32 v137, 0x3e38aa3b, v150
	v_mul_f32_e32 v142, 0x3e38aa3b, v130
	v_cvt_pk_bf16_f32 v130, v131, v134
	v_cvt_pk_bf16_f32 v131, v137, v142
	global_store_dwordx2 v[128:129], v[130:131], off nt
	v_add_u32_e32 v137, 48, v148
	v_lshlrev_b32_e32 v128, 8, v137
	v_and_b32_e32 v134, 0x7fc00, v128
	ds_bpermute_b32 v128, v149, v76
	v_lshl_add_u64 v[150:151], v[140:141], 0, v[134:135]
	ds_bpermute_b32 v134, v149, v72
	ds_bpermute_b32 v154, v149, v68
	v_mov_b32_e32 v152, v76
	s_waitcnt lgkmcnt(2)
	v_mul_f32_e32 v153, v147, v128
	global_load_dwordx4 v[128:131], v[150:151], off offset:16
	global_load_dwordx4 v[142:145], v[150:151], off
	ds_bpermute_b32 v155, v149, v64
	ds_bpermute_b32 v156, v149, v69
	ds_bpermute_b32 v157, v149, v65
	s_waitcnt vmcnt(0)
	v_pk_mul_f32 v[142:143], v[152:153], v[142:143]
	s_nop 0
	v_add_f32_e32 v152, v142, v143
	s_waitcnt lgkmcnt(4)
	v_mul_f32_e32 v143, v147, v134
	v_mov_b32_e32 v142, v72
	v_pk_mul_f32 v[142:143], v[142:143], v[144:145]
	s_nop 0
	v_add_f32_e32 v134, v142, v143
	s_waitcnt lgkmcnt(3)
	v_mul_f32_e32 v143, v147, v154
	v_mov_b32_e32 v142, v68
	v_pk_mul_f32 v[128:129], v[142:143], v[128:129]
	v_mad_i64_i32 v[142:143], s[24:25], v137, s13, v[138:139]
	v_add_f32_e32 v144, v128, v129
	s_waitcnt lgkmcnt(2)
	v_mul_f32_e32 v129, v147, v155
	v_mov_b32_e32 v128, v64
	v_pk_mul_f32 v[128:129], v[128:129], v[130:131]
	v_mul_f32_e32 v131, 0x3e38aa3b, v144
	v_add_f32_e32 v128, v128, v129
	v_mul_f32_e32 v128, 0x3e38aa3b, v128
	v_cvt_pk_bf16_f32 v145, v131, v128
	ds_bpermute_b32 v128, v149, v77
	v_mul_f32_e32 v129, 0x3e38aa3b, v152
	v_mul_f32_e32 v130, 0x3e38aa3b, v134
	v_cvt_pk_bf16_f32 v144, v129, v130
	ds_bpermute_b32 v137, v149, v73
	s_waitcnt lgkmcnt(1)
	v_mul_f32_e32 v155, v147, v128
	global_load_dwordx4 v[128:131], v[150:151], off offset:272
	s_nop 0
	global_load_dwordx4 v[150:153], v[150:151], off offset:256
	v_mov_b32_e32 v154, v77
	v_add_u32_e32 v134, 49, v148
	global_store_dwordx2 v[142:143], v[144:145], off nt
	s_waitcnt vmcnt(1)
	v_pk_mul_f32 v[150:151], v[154:155], v[150:151]
	s_nop 0
	v_add_f32_e32 v154, v150, v151
	s_waitcnt lgkmcnt(0)
	v_mul_f32_e32 v151, v147, v137
	v_mov_b32_e32 v150, v73
	v_pk_mul_f32 v[150:151], v[150:151], v[152:153]
	s_nop 0
	v_add_f32_e32 v137, v150, v151
	v_mul_f32_e32 v151, v147, v156
	v_mov_b32_e32 v150, v69
	v_pk_mul_f32 v[128:129], v[150:151], v[128:129]
	s_nop 0
	v_add_f32_e32 v150, v128, v129
	v_mul_f32_e32 v129, v147, v157
	v_mov_b32_e32 v128, v65
	v_pk_mul_f32 v[128:129], v[128:129], v[130:131]
	v_mul_f32_e32 v131, 0x3e38aa3b, v154
	v_add_f32_e32 v130, v128, v129
	v_mad_i64_i32 v[128:129], s[24:25], v134, s13, v[138:139]
	v_mul_f32_e32 v134, 0x3e38aa3b, v137
	v_mul_f32_e32 v137, 0x3e38aa3b, v150
	v_mul_f32_e32 v142, 0x3e38aa3b, v130
	v_cvt_pk_bf16_f32 v130, v131, v134
	v_cvt_pk_bf16_f32 v131, v137, v142
	global_store_dwordx2 v[128:129], v[130:131], off nt
	v_add_u32_e32 v137, 50, v148
	v_lshlrev_b32_e32 v128, 8, v137
	v_and_b32_e32 v134, 0x7fe00, v128
	ds_bpermute_b32 v128, v149, v78
	v_lshl_add_u64 v[150:151], v[140:141], 0, v[134:135]
	ds_bpermute_b32 v134, v149, v74
	ds_bpermute_b32 v154, v149, v70
	v_mov_b32_e32 v152, v78
	s_waitcnt lgkmcnt(2)
	v_mul_f32_e32 v153, v147, v128
	global_load_dwordx4 v[128:131], v[150:151], off offset:16
	global_load_dwordx4 v[142:145], v[150:151], off
	ds_bpermute_b32 v155, v149, v66
	ds_bpermute_b32 v156, v149, v71
	ds_bpermute_b32 v157, v149, v67
	s_waitcnt vmcnt(0)
	v_pk_mul_f32 v[142:143], v[152:153], v[142:143]
	s_nop 0
	v_add_f32_e32 v152, v142, v143
	s_waitcnt lgkmcnt(4)
	v_mul_f32_e32 v143, v147, v134
	v_mov_b32_e32 v142, v74
	v_pk_mul_f32 v[142:143], v[142:143], v[144:145]
	s_nop 0
	v_add_f32_e32 v134, v142, v143
	s_waitcnt lgkmcnt(3)
	v_mul_f32_e32 v143, v147, v154
	v_mov_b32_e32 v142, v70
	v_pk_mul_f32 v[128:129], v[142:143], v[128:129]
	v_mad_i64_i32 v[142:143], s[24:25], v137, s13, v[138:139]
	v_add_f32_e32 v144, v128, v129
	s_waitcnt lgkmcnt(2)
	v_mul_f32_e32 v129, v147, v155
	v_mov_b32_e32 v128, v66
	v_pk_mul_f32 v[128:129], v[128:129], v[130:131]
	v_mul_f32_e32 v131, 0x3e38aa3b, v144
	v_add_f32_e32 v128, v128, v129
	v_mul_f32_e32 v128, 0x3e38aa3b, v128
	v_cvt_pk_bf16_f32 v145, v131, v128
	ds_bpermute_b32 v128, v149, v79
	v_mul_f32_e32 v129, 0x3e38aa3b, v152
	v_mul_f32_e32 v130, 0x3e38aa3b, v134
	v_cvt_pk_bf16_f32 v144, v129, v130
	ds_bpermute_b32 v137, v149, v75
	s_waitcnt lgkmcnt(1)
	v_mul_f32_e32 v155, v147, v128
	global_load_dwordx4 v[128:131], v[150:151], off offset:272
	s_nop 0
	global_load_dwordx4 v[150:153], v[150:151], off offset:256
	v_mov_b32_e32 v154, v79
	v_add_u32_e32 v134, 51, v148
	global_store_dwordx2 v[142:143], v[144:145], off nt
	s_waitcnt vmcnt(1)
	v_pk_mul_f32 v[150:151], v[154:155], v[150:151]
	s_nop 0
	v_add_f32_e32 v154, v150, v151
	s_waitcnt lgkmcnt(0)
	v_mul_f32_e32 v151, v147, v137
	v_mov_b32_e32 v150, v75
	v_pk_mul_f32 v[150:151], v[150:151], v[152:153]
	s_nop 0
	v_add_f32_e32 v137, v150, v151
	v_mul_f32_e32 v151, v147, v156
	v_mov_b32_e32 v150, v71
	v_pk_mul_f32 v[128:129], v[150:151], v[128:129]
	s_nop 0
	v_add_f32_e32 v150, v128, v129
	v_mul_f32_e32 v129, v147, v157
	v_mov_b32_e32 v128, v67
	v_pk_mul_f32 v[128:129], v[128:129], v[130:131]
	v_mul_f32_e32 v131, 0x3e38aa3b, v154
	v_add_f32_e32 v130, v128, v129
	v_mad_i64_i32 v[128:129], s[24:25], v134, s13, v[138:139]
	v_mul_f32_e32 v134, 0x3e38aa3b, v137
	v_mul_f32_e32 v137, 0x3e38aa3b, v150
	v_mul_f32_e32 v142, 0x3e38aa3b, v130
	v_cvt_pk_bf16_f32 v130, v131, v134
	v_cvt_pk_bf16_f32 v131, v137, v142
	global_store_dwordx2 v[128:129], v[130:131], off nt
	v_add_u32_e32 v137, 64, v148
	v_lshlrev_b32_e32 v128, 8, v137
	v_and_b32_e32 v134, 0x7fc00, v128
	ds_bpermute_b32 v128, v149, v60
	v_lshl_add_u64 v[150:151], v[140:141], 0, v[134:135]
	ds_bpermute_b32 v134, v149, v56
	ds_bpermute_b32 v154, v149, v52
	v_mov_b32_e32 v152, v60
	s_waitcnt lgkmcnt(2)
	v_mul_f32_e32 v153, v147, v128
	global_load_dwordx4 v[128:131], v[150:151], off offset:16
	global_load_dwordx4 v[142:145], v[150:151], off
	ds_bpermute_b32 v155, v149, v48
	ds_bpermute_b32 v156, v149, v53
	ds_bpermute_b32 v157, v149, v49
	s_waitcnt vmcnt(0)
	v_pk_mul_f32 v[142:143], v[152:153], v[142:143]
	s_nop 0
	v_add_f32_e32 v152, v142, v143
	s_waitcnt lgkmcnt(4)
	v_mul_f32_e32 v143, v147, v134
	v_mov_b32_e32 v142, v56
	v_pk_mul_f32 v[142:143], v[142:143], v[144:145]
	s_nop 0
	v_add_f32_e32 v134, v142, v143
	s_waitcnt lgkmcnt(3)
	v_mul_f32_e32 v143, v147, v154
	v_mov_b32_e32 v142, v52
	v_pk_mul_f32 v[128:129], v[142:143], v[128:129]
	v_mad_i64_i32 v[142:143], s[24:25], v137, s13, v[138:139]
	v_add_f32_e32 v144, v128, v129
	s_waitcnt lgkmcnt(2)
	v_mul_f32_e32 v129, v147, v155
	v_mov_b32_e32 v128, v48
	v_pk_mul_f32 v[128:129], v[128:129], v[130:131]
	v_mul_f32_e32 v131, 0x3e38aa3b, v144
	v_add_f32_e32 v128, v128, v129
	v_mul_f32_e32 v128, 0x3e38aa3b, v128
	v_cvt_pk_bf16_f32 v145, v131, v128
	ds_bpermute_b32 v128, v149, v61
	v_mul_f32_e32 v129, 0x3e38aa3b, v152
	v_mul_f32_e32 v130, 0x3e38aa3b, v134
	v_cvt_pk_bf16_f32 v144, v129, v130
	ds_bpermute_b32 v137, v149, v57
	s_waitcnt lgkmcnt(1)
	v_mul_f32_e32 v155, v147, v128
	global_load_dwordx4 v[128:131], v[150:151], off offset:272
	s_nop 0
	global_load_dwordx4 v[150:153], v[150:151], off offset:256
	v_mov_b32_e32 v154, v61
	v_add_u32_e32 v134, 0x41, v148
	global_store_dwordx2 v[142:143], v[144:145], off nt
	s_waitcnt vmcnt(1)
	v_pk_mul_f32 v[150:151], v[154:155], v[150:151]
	s_nop 0
	v_add_f32_e32 v154, v150, v151
	s_waitcnt lgkmcnt(0)
	v_mul_f32_e32 v151, v147, v137
	v_mov_b32_e32 v150, v57
	v_pk_mul_f32 v[150:151], v[150:151], v[152:153]
	s_nop 0
	v_add_f32_e32 v137, v150, v151
	v_mul_f32_e32 v151, v147, v156
	v_mov_b32_e32 v150, v53
	v_pk_mul_f32 v[128:129], v[150:151], v[128:129]
	s_nop 0
	v_add_f32_e32 v150, v128, v129
	v_mul_f32_e32 v129, v147, v157
	v_mov_b32_e32 v128, v49
	v_pk_mul_f32 v[128:129], v[128:129], v[130:131]
	v_mul_f32_e32 v131, 0x3e38aa3b, v154
	v_add_f32_e32 v130, v128, v129
	v_mad_i64_i32 v[128:129], s[24:25], v134, s13, v[138:139]
	v_mul_f32_e32 v134, 0x3e38aa3b, v137
	v_mul_f32_e32 v137, 0x3e38aa3b, v150
	v_mul_f32_e32 v142, 0x3e38aa3b, v130
	v_cvt_pk_bf16_f32 v130, v131, v134
	v_cvt_pk_bf16_f32 v131, v137, v142
	global_store_dwordx2 v[128:129], v[130:131], off nt
	v_add_u32_e32 v137, 0x42, v148
	v_lshlrev_b32_e32 v128, 8, v137
	v_and_b32_e32 v134, 0x7fe00, v128
	ds_bpermute_b32 v128, v149, v62
	v_lshl_add_u64 v[150:151], v[140:141], 0, v[134:135]
	ds_bpermute_b32 v134, v149, v58
	ds_bpermute_b32 v154, v149, v54
	v_mov_b32_e32 v152, v62
	s_waitcnt lgkmcnt(2)
	v_mul_f32_e32 v153, v147, v128
	global_load_dwordx4 v[128:131], v[150:151], off offset:16
	global_load_dwordx4 v[142:145], v[150:151], off
	ds_bpermute_b32 v155, v149, v50
	ds_bpermute_b32 v156, v149, v55
	ds_bpermute_b32 v157, v149, v51
	s_waitcnt vmcnt(0)
	v_pk_mul_f32 v[142:143], v[152:153], v[142:143]
	s_nop 0
	v_add_f32_e32 v152, v142, v143
	s_waitcnt lgkmcnt(4)
	v_mul_f32_e32 v143, v147, v134
	v_mov_b32_e32 v142, v58
	v_pk_mul_f32 v[142:143], v[142:143], v[144:145]
	s_nop 0
	v_add_f32_e32 v134, v142, v143
	s_waitcnt lgkmcnt(3)
	v_mul_f32_e32 v143, v147, v154
	v_mov_b32_e32 v142, v54
	v_pk_mul_f32 v[128:129], v[142:143], v[128:129]
	v_mad_i64_i32 v[142:143], s[24:25], v137, s13, v[138:139]
	v_add_f32_e32 v144, v128, v129
	s_waitcnt lgkmcnt(2)
	v_mul_f32_e32 v129, v147, v155
	v_mov_b32_e32 v128, v50
	v_pk_mul_f32 v[128:129], v[128:129], v[130:131]
	v_mul_f32_e32 v131, 0x3e38aa3b, v144
	v_add_f32_e32 v128, v128, v129
	v_mul_f32_e32 v128, 0x3e38aa3b, v128
	v_cvt_pk_bf16_f32 v145, v131, v128
	ds_bpermute_b32 v128, v149, v63
	v_mul_f32_e32 v129, 0x3e38aa3b, v152
	v_mul_f32_e32 v130, 0x3e38aa3b, v134
	v_cvt_pk_bf16_f32 v144, v129, v130
	ds_bpermute_b32 v137, v149, v59
	s_waitcnt lgkmcnt(1)
	v_mul_f32_e32 v155, v147, v128
	global_load_dwordx4 v[128:131], v[150:151], off offset:272
	s_nop 0
	global_load_dwordx4 v[150:153], v[150:151], off offset:256
	v_mov_b32_e32 v154, v63
	v_add_u32_e32 v134, 0x43, v148
	global_store_dwordx2 v[142:143], v[144:145], off nt
	s_waitcnt vmcnt(1)
	v_pk_mul_f32 v[150:151], v[154:155], v[150:151]
	s_nop 0
	v_add_f32_e32 v154, v150, v151
	s_waitcnt lgkmcnt(0)
	v_mul_f32_e32 v151, v147, v137
	v_mov_b32_e32 v150, v59
	v_pk_mul_f32 v[150:151], v[150:151], v[152:153]
	s_nop 0
	v_add_f32_e32 v137, v150, v151
	v_mul_f32_e32 v151, v147, v156
	v_mov_b32_e32 v150, v55
	v_pk_mul_f32 v[128:129], v[150:151], v[128:129]
	s_nop 0
	v_add_f32_e32 v150, v128, v129
	v_mul_f32_e32 v129, v147, v157
	v_mov_b32_e32 v128, v51
	v_pk_mul_f32 v[128:129], v[128:129], v[130:131]
	v_mul_f32_e32 v131, 0x3e38aa3b, v154
	v_add_f32_e32 v130, v128, v129
	v_mad_i64_i32 v[128:129], s[24:25], v134, s13, v[138:139]
	v_mul_f32_e32 v134, 0x3e38aa3b, v137
	v_mul_f32_e32 v137, 0x3e38aa3b, v150
	v_mul_f32_e32 v142, 0x3e38aa3b, v130
	v_cvt_pk_bf16_f32 v130, v131, v134
	v_cvt_pk_bf16_f32 v131, v137, v142
	global_store_dwordx2 v[128:129], v[130:131], off nt
	v_add_u32_e32 v137, 0x50, v148
	v_lshlrev_b32_e32 v128, 8, v137
	v_and_b32_e32 v134, 0x7fc00, v128
	ds_bpermute_b32 v128, v149, v44
	v_lshl_add_u64 v[150:151], v[140:141], 0, v[134:135]
	ds_bpermute_b32 v134, v149, v40
	ds_bpermute_b32 v154, v149, v36
	v_mov_b32_e32 v152, v44
	s_waitcnt lgkmcnt(2)
	v_mul_f32_e32 v153, v147, v128
	global_load_dwordx4 v[128:131], v[150:151], off offset:16
	global_load_dwordx4 v[142:145], v[150:151], off
	ds_bpermute_b32 v155, v149, v32
	ds_bpermute_b32 v156, v149, v37
	ds_bpermute_b32 v157, v149, v33
	s_waitcnt vmcnt(0)
	v_pk_mul_f32 v[142:143], v[152:153], v[142:143]
	s_nop 0
	v_add_f32_e32 v152, v142, v143
	s_waitcnt lgkmcnt(4)
	v_mul_f32_e32 v143, v147, v134
	v_mov_b32_e32 v142, v40
	v_pk_mul_f32 v[142:143], v[142:143], v[144:145]
	s_nop 0
	v_add_f32_e32 v134, v142, v143
	s_waitcnt lgkmcnt(3)
	v_mul_f32_e32 v143, v147, v154
	v_mov_b32_e32 v142, v36
	v_pk_mul_f32 v[128:129], v[142:143], v[128:129]
	v_mad_i64_i32 v[142:143], s[24:25], v137, s13, v[138:139]
	v_add_f32_e32 v144, v128, v129
	s_waitcnt lgkmcnt(2)
	v_mul_f32_e32 v129, v147, v155
	v_mov_b32_e32 v128, v32
	v_pk_mul_f32 v[128:129], v[128:129], v[130:131]
	v_mul_f32_e32 v131, 0x3e38aa3b, v144
	v_add_f32_e32 v128, v128, v129
	v_mul_f32_e32 v128, 0x3e38aa3b, v128
	v_cvt_pk_bf16_f32 v145, v131, v128
	ds_bpermute_b32 v128, v149, v45
	v_mul_f32_e32 v129, 0x3e38aa3b, v152
	v_mul_f32_e32 v130, 0x3e38aa3b, v134
	v_cvt_pk_bf16_f32 v144, v129, v130
	ds_bpermute_b32 v137, v149, v41
	s_waitcnt lgkmcnt(1)
	v_mul_f32_e32 v155, v147, v128
	global_load_dwordx4 v[128:131], v[150:151], off offset:272
	s_nop 0
	global_load_dwordx4 v[150:153], v[150:151], off offset:256
	v_mov_b32_e32 v154, v45
	v_add_u32_e32 v134, 0x51, v148
	global_store_dwordx2 v[142:143], v[144:145], off nt
	s_waitcnt vmcnt(1)
	v_pk_mul_f32 v[150:151], v[154:155], v[150:151]
	s_nop 0
	v_add_f32_e32 v154, v150, v151
	s_waitcnt lgkmcnt(0)
	v_mul_f32_e32 v151, v147, v137
	v_mov_b32_e32 v150, v41
	v_pk_mul_f32 v[150:151], v[150:151], v[152:153]
	s_nop 0
	v_add_f32_e32 v137, v150, v151
	v_mul_f32_e32 v151, v147, v156
	v_mov_b32_e32 v150, v37
	v_pk_mul_f32 v[128:129], v[150:151], v[128:129]
	s_nop 0
	v_add_f32_e32 v150, v128, v129
	v_mul_f32_e32 v129, v147, v157
	v_mov_b32_e32 v128, v33
	v_pk_mul_f32 v[128:129], v[128:129], v[130:131]
	v_mul_f32_e32 v131, 0x3e38aa3b, v154
	v_add_f32_e32 v130, v128, v129
	v_mad_i64_i32 v[128:129], s[24:25], v134, s13, v[138:139]
	v_mul_f32_e32 v134, 0x3e38aa3b, v137
	v_mul_f32_e32 v137, 0x3e38aa3b, v150
	v_mul_f32_e32 v142, 0x3e38aa3b, v130
	v_cvt_pk_bf16_f32 v130, v131, v134
	v_cvt_pk_bf16_f32 v131, v137, v142
	global_store_dwordx2 v[128:129], v[130:131], off nt
	v_add_u32_e32 v137, 0x52, v148
	v_lshlrev_b32_e32 v128, 8, v137
	v_and_b32_e32 v134, 0x7fe00, v128
	ds_bpermute_b32 v128, v149, v46
	v_lshl_add_u64 v[150:151], v[140:141], 0, v[134:135]
	ds_bpermute_b32 v134, v149, v42
	ds_bpermute_b32 v154, v149, v38
	v_mov_b32_e32 v152, v46
	s_waitcnt lgkmcnt(2)
	v_mul_f32_e32 v153, v147, v128
	global_load_dwordx4 v[128:131], v[150:151], off offset:16
	global_load_dwordx4 v[142:145], v[150:151], off
	ds_bpermute_b32 v155, v149, v34
	ds_bpermute_b32 v156, v149, v39
	ds_bpermute_b32 v157, v149, v35
	s_waitcnt vmcnt(0)
	v_pk_mul_f32 v[142:143], v[152:153], v[142:143]
	s_nop 0
	v_add_f32_e32 v152, v142, v143
	s_waitcnt lgkmcnt(4)
	v_mul_f32_e32 v143, v147, v134
	v_mov_b32_e32 v142, v42
	v_pk_mul_f32 v[142:143], v[142:143], v[144:145]
	s_nop 0
	v_add_f32_e32 v134, v142, v143
	s_waitcnt lgkmcnt(3)
	v_mul_f32_e32 v143, v147, v154
	v_mov_b32_e32 v142, v38
	v_pk_mul_f32 v[128:129], v[142:143], v[128:129]
	v_mad_i64_i32 v[142:143], s[24:25], v137, s13, v[138:139]
	v_add_f32_e32 v144, v128, v129
	s_waitcnt lgkmcnt(2)
	v_mul_f32_e32 v129, v147, v155
	v_mov_b32_e32 v128, v34
	v_pk_mul_f32 v[128:129], v[128:129], v[130:131]
	v_mul_f32_e32 v131, 0x3e38aa3b, v144
	v_add_f32_e32 v128, v128, v129
	v_mul_f32_e32 v128, 0x3e38aa3b, v128
	v_cvt_pk_bf16_f32 v145, v131, v128
	ds_bpermute_b32 v128, v149, v47
	v_mul_f32_e32 v129, 0x3e38aa3b, v152
	v_mul_f32_e32 v130, 0x3e38aa3b, v134
	v_cvt_pk_bf16_f32 v144, v129, v130
	ds_bpermute_b32 v137, v149, v43
	s_waitcnt lgkmcnt(1)
	v_mul_f32_e32 v155, v147, v128
	global_load_dwordx4 v[128:131], v[150:151], off offset:272
	s_nop 0
	global_load_dwordx4 v[150:153], v[150:151], off offset:256
	v_mov_b32_e32 v154, v47
	v_add_u32_e32 v134, 0x53, v148
	global_store_dwordx2 v[142:143], v[144:145], off nt
	s_waitcnt vmcnt(1)
	v_pk_mul_f32 v[150:151], v[154:155], v[150:151]
	s_nop 0
	v_add_f32_e32 v154, v150, v151
	s_waitcnt lgkmcnt(0)
	v_mul_f32_e32 v151, v147, v137
	v_mov_b32_e32 v150, v43
	v_pk_mul_f32 v[150:151], v[150:151], v[152:153]
	s_nop 0
	v_add_f32_e32 v137, v150, v151
	v_mul_f32_e32 v151, v147, v156
	v_mov_b32_e32 v150, v39
	v_pk_mul_f32 v[128:129], v[150:151], v[128:129]
	s_nop 0
	v_add_f32_e32 v150, v128, v129
	v_mul_f32_e32 v129, v147, v157
	v_mov_b32_e32 v128, v35
	v_pk_mul_f32 v[128:129], v[128:129], v[130:131]
	v_mul_f32_e32 v131, 0x3e38aa3b, v154
	v_add_f32_e32 v130, v128, v129
	v_mad_i64_i32 v[128:129], s[24:25], v134, s13, v[138:139]
	v_mul_f32_e32 v134, 0x3e38aa3b, v137
	v_mul_f32_e32 v137, 0x3e38aa3b, v150
	v_mul_f32_e32 v142, 0x3e38aa3b, v130
	v_cvt_pk_bf16_f32 v130, v131, v134
	v_cvt_pk_bf16_f32 v131, v137, v142
	global_store_dwordx2 v[128:129], v[130:131], off nt
	v_add_u32_e32 v137, 0x60, v148
	v_lshlrev_b32_e32 v128, 8, v137
	v_and_b32_e32 v134, 0x7fc00, v128
	ds_bpermute_b32 v128, v149, v28
	v_lshl_add_u64 v[150:151], v[140:141], 0, v[134:135]
	ds_bpermute_b32 v134, v149, v24
	ds_bpermute_b32 v154, v149, v20
	v_mov_b32_e32 v152, v28
	s_waitcnt lgkmcnt(2)
	v_mul_f32_e32 v153, v147, v128
	global_load_dwordx4 v[128:131], v[150:151], off offset:16
	global_load_dwordx4 v[142:145], v[150:151], off
	ds_bpermute_b32 v155, v149, v16
	ds_bpermute_b32 v156, v149, v21
	ds_bpermute_b32 v157, v149, v17
	s_waitcnt vmcnt(0)
	v_pk_mul_f32 v[142:143], v[152:153], v[142:143]
	s_nop 0
	v_add_f32_e32 v152, v142, v143
	s_waitcnt lgkmcnt(4)
	v_mul_f32_e32 v143, v147, v134
	v_mov_b32_e32 v142, v24
	v_pk_mul_f32 v[142:143], v[142:143], v[144:145]
	s_nop 0
	v_add_f32_e32 v134, v142, v143
	s_waitcnt lgkmcnt(3)
	v_mul_f32_e32 v143, v147, v154
	v_mov_b32_e32 v142, v20
	v_pk_mul_f32 v[128:129], v[142:143], v[128:129]
	v_mad_i64_i32 v[142:143], s[24:25], v137, s13, v[138:139]
	v_add_f32_e32 v144, v128, v129
	s_waitcnt lgkmcnt(2)
	v_mul_f32_e32 v129, v147, v155
	v_mov_b32_e32 v128, v16
	v_pk_mul_f32 v[128:129], v[128:129], v[130:131]
	v_mul_f32_e32 v131, 0x3e38aa3b, v144
	v_add_f32_e32 v128, v128, v129
	v_mul_f32_e32 v128, 0x3e38aa3b, v128
	v_cvt_pk_bf16_f32 v145, v131, v128
	ds_bpermute_b32 v128, v149, v29
	v_mul_f32_e32 v129, 0x3e38aa3b, v152
	v_mul_f32_e32 v130, 0x3e38aa3b, v134
	v_cvt_pk_bf16_f32 v144, v129, v130
	ds_bpermute_b32 v137, v149, v25
	s_waitcnt lgkmcnt(1)
	v_mul_f32_e32 v155, v147, v128
	global_load_dwordx4 v[128:131], v[150:151], off offset:272
	s_nop 0
	global_load_dwordx4 v[150:153], v[150:151], off offset:256
	v_mov_b32_e32 v154, v29
	v_add_u32_e32 v134, 0x61, v148
	global_store_dwordx2 v[142:143], v[144:145], off nt
	s_waitcnt vmcnt(1)
	v_pk_mul_f32 v[150:151], v[154:155], v[150:151]
	s_nop 0
	v_add_f32_e32 v154, v150, v151
	s_waitcnt lgkmcnt(0)
	v_mul_f32_e32 v151, v147, v137
	v_mov_b32_e32 v150, v25
	v_pk_mul_f32 v[150:151], v[150:151], v[152:153]
	s_nop 0
	v_add_f32_e32 v137, v150, v151
	v_mul_f32_e32 v151, v147, v156
	v_mov_b32_e32 v150, v21
	v_pk_mul_f32 v[128:129], v[150:151], v[128:129]
	s_nop 0
	v_add_f32_e32 v150, v128, v129
	v_mul_f32_e32 v129, v147, v157
	v_mov_b32_e32 v128, v17
	v_pk_mul_f32 v[128:129], v[128:129], v[130:131]
	v_mul_f32_e32 v131, 0x3e38aa3b, v154
	v_add_f32_e32 v130, v128, v129
	v_mad_i64_i32 v[128:129], s[24:25], v134, s13, v[138:139]
	v_mul_f32_e32 v134, 0x3e38aa3b, v137
	v_mul_f32_e32 v137, 0x3e38aa3b, v150
	v_mul_f32_e32 v142, 0x3e38aa3b, v130
	v_cvt_pk_bf16_f32 v130, v131, v134
	v_cvt_pk_bf16_f32 v131, v137, v142
	global_store_dwordx2 v[128:129], v[130:131], off nt
	v_add_u32_e32 v137, 0x62, v148
	v_lshlrev_b32_e32 v128, 8, v137
	v_and_b32_e32 v134, 0x7fe00, v128
	ds_bpermute_b32 v128, v149, v30
	v_lshl_add_u64 v[150:151], v[140:141], 0, v[134:135]
	ds_bpermute_b32 v134, v149, v26
	ds_bpermute_b32 v154, v149, v22
	v_mov_b32_e32 v152, v30
	s_waitcnt lgkmcnt(2)
	v_mul_f32_e32 v153, v147, v128
	global_load_dwordx4 v[128:131], v[150:151], off offset:16
	global_load_dwordx4 v[142:145], v[150:151], off
	ds_bpermute_b32 v155, v149, v18
	ds_bpermute_b32 v156, v149, v23
	ds_bpermute_b32 v157, v149, v19
	s_waitcnt vmcnt(0)
	v_pk_mul_f32 v[142:143], v[152:153], v[142:143]
	s_nop 0
	v_add_f32_e32 v152, v142, v143
	s_waitcnt lgkmcnt(4)
	v_mul_f32_e32 v143, v147, v134
	v_mov_b32_e32 v142, v26
	v_pk_mul_f32 v[142:143], v[142:143], v[144:145]
	s_nop 0
	v_add_f32_e32 v134, v142, v143
	s_waitcnt lgkmcnt(3)
	v_mul_f32_e32 v143, v147, v154
	v_mov_b32_e32 v142, v22
	v_pk_mul_f32 v[128:129], v[142:143], v[128:129]
	v_mad_i64_i32 v[142:143], s[24:25], v137, s13, v[138:139]
	v_add_f32_e32 v144, v128, v129
	s_waitcnt lgkmcnt(2)
	v_mul_f32_e32 v129, v147, v155
	v_mov_b32_e32 v128, v18
	v_pk_mul_f32 v[128:129], v[128:129], v[130:131]
	v_mul_f32_e32 v131, 0x3e38aa3b, v144
	v_add_f32_e32 v128, v128, v129
	v_mul_f32_e32 v128, 0x3e38aa3b, v128
	v_cvt_pk_bf16_f32 v145, v131, v128
	ds_bpermute_b32 v128, v149, v31
	v_mul_f32_e32 v129, 0x3e38aa3b, v152
	v_mul_f32_e32 v130, 0x3e38aa3b, v134
	v_cvt_pk_bf16_f32 v144, v129, v130
	ds_bpermute_b32 v137, v149, v27
	s_waitcnt lgkmcnt(1)
	v_mul_f32_e32 v155, v147, v128
	global_load_dwordx4 v[128:131], v[150:151], off offset:272
	s_nop 0
	global_load_dwordx4 v[150:153], v[150:151], off offset:256
	v_mov_b32_e32 v154, v31
	v_add_u32_e32 v134, 0x63, v148
	global_store_dwordx2 v[142:143], v[144:145], off nt
	s_waitcnt vmcnt(1)
	v_pk_mul_f32 v[150:151], v[154:155], v[150:151]
	s_nop 0
	v_add_f32_e32 v154, v150, v151
	s_waitcnt lgkmcnt(0)
	v_mul_f32_e32 v151, v147, v137
	v_mov_b32_e32 v150, v27
	v_pk_mul_f32 v[150:151], v[150:151], v[152:153]
	s_nop 0
	v_add_f32_e32 v137, v150, v151
	v_mul_f32_e32 v151, v147, v156
	v_mov_b32_e32 v150, v23
	v_pk_mul_f32 v[128:129], v[150:151], v[128:129]
	s_nop 0
	v_add_f32_e32 v150, v128, v129
	v_mul_f32_e32 v129, v147, v157
	v_mov_b32_e32 v128, v19
	v_pk_mul_f32 v[128:129], v[128:129], v[130:131]
	v_mul_f32_e32 v131, 0x3e38aa3b, v154
	v_add_f32_e32 v130, v128, v129
	v_mad_i64_i32 v[128:129], s[24:25], v134, s13, v[138:139]
	v_mul_f32_e32 v134, 0x3e38aa3b, v137
	v_mul_f32_e32 v137, 0x3e38aa3b, v150
	v_mul_f32_e32 v142, 0x3e38aa3b, v130
	v_cvt_pk_bf16_f32 v130, v131, v134
	v_cvt_pk_bf16_f32 v131, v137, v142
	global_store_dwordx2 v[128:129], v[130:131], off nt
	v_add_u32_e32 v137, 0x70, v148
	v_lshlrev_b32_e32 v128, 8, v137
	v_and_b32_e32 v134, 0x7fc00, v128
	ds_bpermute_b32 v128, v149, v12
	v_lshl_add_u64 v[150:151], v[140:141], 0, v[134:135]
	ds_bpermute_b32 v134, v149, v8
	ds_bpermute_b32 v154, v149, v4
	v_mov_b32_e32 v152, v12
	s_waitcnt lgkmcnt(2)
	v_mul_f32_e32 v153, v147, v128
	global_load_dwordx4 v[128:131], v[150:151], off offset:16
	global_load_dwordx4 v[142:145], v[150:151], off
	ds_bpermute_b32 v155, v149, v0
	ds_bpermute_b32 v156, v149, v5
	ds_bpermute_b32 v157, v149, v1
	s_waitcnt vmcnt(0)
	v_pk_mul_f32 v[142:143], v[152:153], v[142:143]
	s_nop 0
	v_add_f32_e32 v152, v142, v143
	s_waitcnt lgkmcnt(4)
	v_mul_f32_e32 v143, v147, v134
	v_mov_b32_e32 v142, v8
	v_pk_mul_f32 v[142:143], v[142:143], v[144:145]
	s_nop 0
	v_add_f32_e32 v134, v142, v143
	s_waitcnt lgkmcnt(3)
	v_mul_f32_e32 v143, v147, v154
	v_mov_b32_e32 v142, v4
	v_pk_mul_f32 v[128:129], v[142:143], v[128:129]
	v_mad_i64_i32 v[142:143], s[24:25], v137, s13, v[138:139]
	v_add_f32_e32 v144, v128, v129
	s_waitcnt lgkmcnt(2)
	v_mul_f32_e32 v129, v147, v155
	v_mov_b32_e32 v128, v0
	v_pk_mul_f32 v[128:129], v[128:129], v[130:131]
	v_mul_f32_e32 v131, 0x3e38aa3b, v144
	v_add_f32_e32 v128, v128, v129
	v_mul_f32_e32 v128, 0x3e38aa3b, v128
	v_cvt_pk_bf16_f32 v145, v131, v128
	ds_bpermute_b32 v128, v149, v13
	v_mul_f32_e32 v129, 0x3e38aa3b, v152
	v_mul_f32_e32 v130, 0x3e38aa3b, v134
	v_cvt_pk_bf16_f32 v144, v129, v130
	ds_bpermute_b32 v137, v149, v9
	s_waitcnt lgkmcnt(1)
	v_mul_f32_e32 v155, v147, v128
	global_load_dwordx4 v[128:131], v[150:151], off offset:272
	s_nop 0
	global_load_dwordx4 v[150:153], v[150:151], off offset:256
	v_mov_b32_e32 v154, v13
	v_add_u32_e32 v134, 0x71, v148
	global_store_dwordx2 v[142:143], v[144:145], off nt
	s_waitcnt vmcnt(1)
	v_pk_mul_f32 v[150:151], v[154:155], v[150:151]
	s_nop 0
	v_add_f32_e32 v154, v150, v151
	s_waitcnt lgkmcnt(0)
	v_mul_f32_e32 v151, v147, v137
	v_mov_b32_e32 v150, v9
	v_pk_mul_f32 v[150:151], v[150:151], v[152:153]
	s_nop 0
	v_add_f32_e32 v137, v150, v151
	v_mul_f32_e32 v151, v147, v156
	v_mov_b32_e32 v150, v5
	v_pk_mul_f32 v[128:129], v[150:151], v[128:129]
	s_nop 0
	v_add_f32_e32 v150, v128, v129
	v_mul_f32_e32 v129, v147, v157
	v_mov_b32_e32 v128, v1
	v_pk_mul_f32 v[128:129], v[128:129], v[130:131]
	v_mul_f32_e32 v131, 0x3e38aa3b, v154
	v_add_f32_e32 v130, v128, v129
	v_mad_i64_i32 v[128:129], s[24:25], v134, s13, v[138:139]
	v_mul_f32_e32 v134, 0x3e38aa3b, v137
	v_mul_f32_e32 v137, 0x3e38aa3b, v150
	v_mul_f32_e32 v142, 0x3e38aa3b, v130
	v_cvt_pk_bf16_f32 v130, v131, v134
	v_cvt_pk_bf16_f32 v131, v137, v142
	global_store_dwordx2 v[128:129], v[130:131], off nt
	v_add_u32_e32 v137, 0x72, v148
	v_lshlrev_b32_e32 v128, 8, v137
	v_and_b32_e32 v134, 0x7fe00, v128
	ds_bpermute_b32 v128, v149, v14
	v_lshl_add_u64 v[144:145], v[140:141], 0, v[134:135]
	ds_bpermute_b32 v134, v149, v10
	ds_bpermute_b32 v152, v149, v6
	v_mov_b32_e32 v150, v14
	s_waitcnt lgkmcnt(2)
	v_mul_f32_e32 v151, v147, v128
	global_load_dwordx4 v[128:131], v[144:145], off offset:16
	global_load_dwordx4 v[140:143], v[144:145], off
	ds_bpermute_b32 v153, v149, v2
	ds_bpermute_b32 v154, v149, v7
	ds_bpermute_b32 v155, v149, v3
	s_waitcnt vmcnt(0)
	v_pk_mul_f32 v[140:141], v[150:151], v[140:141]
	s_nop 0
	v_add_f32_e32 v150, v140, v141
	s_waitcnt lgkmcnt(4)
	v_mul_f32_e32 v141, v147, v134
	v_mov_b32_e32 v140, v10
	v_pk_mul_f32 v[140:141], v[140:141], v[142:143]
	s_nop 0
	v_add_f32_e32 v134, v140, v141
	s_waitcnt lgkmcnt(3)
	v_mul_f32_e32 v141, v147, v152
	v_mov_b32_e32 v140, v6
	v_pk_mul_f32 v[128:129], v[140:141], v[128:129]
	v_mad_i64_i32 v[140:141], s[24:25], v137, s13, v[138:139]
	v_add_f32_e32 v142, v128, v129
	s_waitcnt lgkmcnt(2)
	v_mul_f32_e32 v129, v147, v153
	v_mov_b32_e32 v128, v2
	v_pk_mul_f32 v[128:129], v[128:129], v[130:131]
	v_mul_f32_e32 v131, 0x3e38aa3b, v142
	v_add_f32_e32 v128, v128, v129
	v_mul_f32_e32 v128, 0x3e38aa3b, v128
	v_cvt_pk_bf16_f32 v143, v131, v128
	ds_bpermute_b32 v128, v149, v15
	v_mul_f32_e32 v129, 0x3e38aa3b, v150
	v_mul_f32_e32 v130, 0x3e38aa3b, v134
	v_cvt_pk_bf16_f32 v142, v129, v130
	v_add_u32_e32 v134, 0x73, v148
	ds_bpermute_b32 v137, v149, v11
	s_waitcnt lgkmcnt(1)
	v_mul_f32_e32 v153, v147, v128
	global_load_dwordx4 v[128:131], v[144:145], off offset:272
	global_load_dwordx4 v[148:151], v[144:145], off offset:256
	v_mov_b32_e32 v152, v15
	global_store_dwordx2 v[140:141], v[142:143], off nt
	s_waitcnt vmcnt(1)
	v_pk_mul_f32 v[144:145], v[152:153], v[148:149]
	s_nop 0
	v_add_f32_e32 v148, v144, v145
	s_waitcnt lgkmcnt(0)
	v_mul_f32_e32 v145, v147, v137
	v_mov_b32_e32 v144, v11
	v_pk_mul_f32 v[144:145], v[144:145], v[150:151]
	s_nop 0
	v_add_f32_e32 v137, v144, v145
	v_mul_f32_e32 v145, v147, v154
	v_mov_b32_e32 v144, v7
	v_pk_mul_f32 v[128:129], v[144:145], v[128:129]
	s_nop 0
	v_add_f32_e32 v144, v128, v129
	v_mul_f32_e32 v129, v147, v155
	v_mov_b32_e32 v128, v3
	v_pk_mul_f32 v[128:129], v[128:129], v[130:131]
	v_mul_f32_e32 v131, 0x3e38aa3b, v148
	v_add_f32_e32 v130, v128, v129
	v_mad_i64_i32 v[128:129], s[24:25], v134, s13, v[138:139]
	s_xor_b64 s[74:75], exec, -1
	v_mul_f32_e32 v134, 0x3e38aa3b, v137
	v_mul_f32_e32 v137, 0x3e38aa3b, v144
	v_mul_f32_e32 v138, 0x3e38aa3b, v130
	v_cvt_pk_bf16_f32 v130, v131, v134
	v_cvt_pk_bf16_f32 v131, v137, v138
	global_store_dwordx2 v[128:129], v[130:131], off

.LBB0_510:
	global_load_dwordx2 v[170:171], v[170:171], off
	v_lshlrev_b32_e32 v134, 2, v168
	v_lshl_add_u64 v[168:169], s[4:5], 0, v[134:135]
	v_lshl_add_u64 v[168:169], v[136:137], 2, v[168:169]
	s_waitcnt vmcnt(0)
	v_lshl_add_u64 v[170:171], v[136:137], 1, v[170:171]
	v_mad_i64_i32 v[172:173], s[24:25], v128, s13, v[170:171]
	v_and_b32_e32 v131, 0x7fc, v128
	v_cvt_pk_bf16_f32 v178, v124, v120
	v_cvt_pk_bf16_f32 v179, v116, v112
	global_store_dwordx2 v[172:173], v[178:179], off
	v_ashrrev_i32_e32 v172, 11, v128
	v_cmp_lt_u32_e32 vcc, s19, v131
	v_ashrrev_i32_e32 v173, 31, v172
	s_and_saveexec_b64 s[66:67], vcc
	s_cbranch_execz .LBB0_512
	v_lshlrev_b64 v[178:179], 9, v[172:173]
	v_add_u32_e32 v134, 0xfffffa00, v131
	v_lshl_add_u64 v[178:179], v[178:179], 0, v[134:135]
	v_mad_u64_u32 v[182:183], s[24:25], v178, s14, v[168:169]
	v_mad_i32_i24 v183, v179, s14, v183
	v_mov_b32_e32 v178, v124
	v_mov_b32_e32 v179, v120
	v_mov_b32_e32 v180, v116
	v_mov_b32_e32 v181, v112
	global_store_dwordx4 v[182:183], v[178:181], off nt
